# up-proj epilogue all 8 row groups merged to 16 B stores; GLA chunk-state and cross-attention outputs stored as 16 B; dilated outputs staged through LDS for full-line stores
# speedup vs baseline: 1.0305x; 1.0022x over previous
; __device__ __forceinline__ unsigned cvt_pk_bf16(float lo, float hi) { unsigned r; asm volatile("v_cvt_pk_bf16_f32 %0, %1, %2" : "=v"(r) : "v"(lo), "v"(hi)); return r; }
;     __device__ __forceinline__ void operator()(const f32x4 (&acc)[2][2][4][2], const Unit& u, int wr, int wc, int fr, int fq) const {
;     ...
;             for (int m = 0; m < 4; ++m) rs[ai][m] = __builtin_amdgcn_rsqf((float)ss[u.pm * BM + ai * HALF + wr * 64 + m * 16 + fr] * (1.f / (2048.f * 262144.f)) + 1e-6f);
; #pragma unroll
;         for (int n = 0; n < 2; ++n) {
;             const int cbase = 128 * u.pn + 32 * wc + 16 * n + 4 * fq;
;             const f32x4 w0 = *(const f32x4*)(cw + cbase), w1 = *(const f32x4*)(cw + FF + cbase), w2 = *(const f32x4*)(cw + 2 * FF + cbase), b4 = *(const f32x4*)(cb + cbase);
; #pragma unroll
;             for (int ai = 0; ai < 2; ++ai) {
;                 const int slab = u.pm * 4 + 2 * ai + wr;
;                 f32x4 r1p = (f32x4){0.f, 0.f, 0.f, 0.f}, r2p = (f32x4){0.f, 0.f, 0.f, 0.f};
; #pragma unroll
;                 for (int m = 0; m < 4; ++m) {
;                     const f32x4 g = acc[ai][1][m][n] * rs[ai][m], v = acc[ai][0][m][n] * rs[ai][m];
;                     f32x4 r1, r2, a;
; #pragma unroll
;                     for (int e = 0; e < 4; ++e) { r1[e] = __shfl(g[e], src1); r2[e] = __shfl(g[e], src2); }
; #pragma unroll
;                     for (int e = 0; e < 4; ++e) {
;                         const float p1 = fr >= 1 ? r1[e] : r1p[e], p2 = fr >= 2 ? r2[e] : r2p[e];
;                         const float gg = b4[e] + w0[e] * p2 + w1[e] * p1 + w2[e] * g[e];
;                         a[e] = gg * __builtin_amdgcn_rcpf(1.f + __expf(-gg)) * v[e];
;                     }
;                     r1p = r1; r2p = r2;
;                     const size_t row = (size_t)(u.pm * BM + ai * HALF + wr * 64 + m * 16 + fr);
;                     if (m == 0 && fr < 2) {
;                         *(f32x4*)(GF + (size_t)(slab * 2 + fr) * FF + cbase) = g; *(f32x4*)(VF + (size_t)(slab * 2 + fr) * FF + cbase) = v;
;                     } else {
;                         typedef unsigned u32x2v __attribute__((ext_vector_type(2)));
;                         u32x2v w; w.x = cvt_pk_bf16(a[0], a[1]); w.y = cvt_pk_bf16(a[2], a[3]);
;                         *(u32x2v*)(ACT + row * FF + cbase) = w;
.LBB0_41:
	v_lshl_add_u32 v160, s66, 8, v193
	v_ashrrev_i32_e32 v161, 31, v160
	v_mov_b32_e32 v148, v227
	v_bfe_u32 v205, v227, 4, 1
	v_mul_u32_u24_e32 v205, 24, v205
	v_lshl_add_u64 v[114:115], v[160:161], 3, s[56:57]
	global_load_dwordx2 v[146:147], v[114:115], off
	v_lshl_or_b32 v156, s64, 7, v198
	v_ashrrev_i32_e32 v157, 31, v156
	global_load_dwordx2 v[190:191], v[114:115], off offset:128
	global_load_dwordx2 v[188:189], v[114:115], off offset:256
	global_load_dwordx2 v[186:187], v[114:115], off offset:384
	global_load_dwordx2 v[176:177], v[114:115], off offset:1024
	global_load_dwordx2 v[174:175], v[114:115], off offset:1152
	global_load_dwordx2 v[172:173], v[114:115], off offset:1280
	global_load_dwordx2 v[170:171], v[114:115], off offset:1408
	v_lshlrev_b64 v[158:159], 2, v[156:157]
	v_lshl_add_u64 v[166:167], s[52:53], 0, v[158:159]
	v_lshl_add_u64 v[118:119], s[60:61], 0, v[158:159]
	v_lshl_add_u64 v[120:121], s[62:63], 0, v[158:159]
	v_lshl_add_u64 v[164:165], s[54:55], 0, v[158:159]
	global_load_dwordx4 v[114:117], v[166:167], off
	global_load_dwordx4 v[138:141], v[118:119], off
	global_load_dwordx4 v[130:133], v[120:121], off
	s_nop 0
	global_load_dwordx4 v[118:121], v[164:165], off
	s_waitcnt vmcnt(0)
	v_ffbh_u32_e32 v149, v147
	v_min_u32_e32 v149, 32, v149
	v_lshlrev_b64 v[146:147], v149, v[146:147]
	v_min_u32_e32 v146, 1, v146
	v_or_b32_e32 v146, v147, v146
	v_cvt_f32_u32_e32 v146, v146
	v_sub_u32_e32 v149, 32, v149
	v_and_b32_e32 v147, 48, v148
	v_or3_b32 v148, v147, v195, v236
	v_ldexp_f32 v146, v146, v149
	v_fmamk_f32 v146, v146, 0x31000000, v232
	v_rsq_f32_e32 v162, v146
	v_or3_b32 v146, v147, v196, v236
	v_lshlrev_b32_e32 v200, 2, v146
	v_lshlrev_b32_e32 v161, 2, v148
	v_pk_mul_f32 v[146:147], v[134:135], v[162:163] op_sel_hi:[1,0]
	v_pk_mul_f32 v[148:149], v[136:137], v[162:163] op_sel_hi:[1,0]
	ds_bpermute_b32 v163, v200, v146
	ds_bpermute_b32 v179, v161, v146
	ds_bpermute_b32 v181, v161, v147
	ds_bpermute_b32 v201, v200, v147
	ds_bpermute_b32 v183, v161, v148
	ds_bpermute_b32 v202, v200, v148
	ds_bpermute_b32 v185, v161, v149
	ds_bpermute_b32 v203, v200, v149
	s_waitcnt lgkmcnt(7)
	v_pk_mul_f32 v[136:137], v[144:145], v[162:163] op_sel_hi:[1,0]
	v_pk_mul_f32 v[134:135], v[142:143], v[162:163] op_sel_hi:[1,0]
	s_and_saveexec_b64 s[10:11], s[42:43]
	s_xor_b64 s[10:11], exec, s[10:11]
	s_movk_i32 s17, 0x2b00
	s_movk_i32 s84, 0x300
	s_mov_b32 s86, 0x24000
	s_mov_b32 s88, 0x48800000
	s_cbranch_execz .LBB0_43
	v_mov_b32_e32 v142, v149
	v_mov_b32_e32 v143, v141
	v_mov_b32_e32 v184, v133
	s_waitcnt lgkmcnt(1)
	v_pk_mul_f32 v[142:143], v[142:143], v[184:185]
	s_waitcnt lgkmcnt(0)
	v_fma_f32 v144, v117, v203, v121
	v_add_f32_e32 v143, v143, v144
	v_add_f32_e32 v142, v142, v143
	v_mul_f32_e32 v143, 0xbfb8aa3b, v142
	v_exp_f32_e32 v143, v143
	v_mov_b32_e32 v149, v140
	v_mov_b32_e32 v182, v132
	v_mov_b32_e32 v180, v131
	v_add_f32_e32 v143, 1.0, v143
	v_rcp_f32_e32 v143, v143
	v_mov_b32_e32 v178, v130
	v_mul_f32_e32 v142, v142, v143
	v_mul_f32_e32 v144, v137, v142
	v_pk_mul_f32 v[142:143], v[148:149], v[182:183]
	v_fma_f32 v137, v116, v202, v120
	v_add_f32_e32 v137, v143, v137
	v_add_f32_e32 v137, v142, v137
	v_mul_f32_e32 v142, 0xbfb8aa3b, v137
	v_exp_f32_e32 v142, v142
	v_fma_f32 v143, v115, v201, v119
	v_add_f32_e32 v142, 1.0, v142
	v_rcp_f32_e32 v142, v142
	s_nop 0
	v_mul_f32_e32 v137, v137, v142
	v_mul_f32_e32 v142, v136, v137
	v_mov_b32_e32 v136, v147
	v_mov_b32_e32 v137, v139
	v_pk_mul_f32 v[136:137], v[136:137], v[180:181]
	v_mov_b32_e32 v147, v138
	v_add_f32_e32 v137, v137, v143
	v_add_f32_e32 v136, v136, v137
	v_mul_f32_e32 v137, 0xbfb8aa3b, v136
	v_exp_f32_e32 v137, v137
	v_fma_f32 v143, v114, v163, v118
	v_add_f32_e32 v137, 1.0, v137
	v_rcp_f32_e32 v137, v137
	s_nop 0
	v_mul_f32_e32 v136, v136, v137
	v_mul_f32_e32 v135, v135, v136
	v_pk_mul_f32 v[136:137], v[146:147], v[178:179]
	s_nop 0
	v_add_f32_e32 v137, v137, v143
	v_add_f32_e32 v136, v136, v137
	v_mul_f32_e32 v137, 0xbfb8aa3b, v136
	v_exp_f32_e32 v137, v137
	s_nop 0
	v_add_f32_e32 v137, 1.0, v137
	v_rcp_f32_e32 v137, v137
	s_nop 0
	v_mul_f32_e32 v136, v136, v137
	v_mul_f32_e32 v134, v134, v136
	v_mov_b64_e32 v[136:137], s[48:49]
	v_mad_i64_i32 v[136:137], s[12:13], v160, s17, v[136:137]
	v_cvt_pk_bf16_f32 v134, v134, v135
	v_cvt_pk_bf16_f32 v135, v142, v144
	v_lshl_add_u64 v[136:137], v[156:157], 1, v[136:137]
	v_mov_b32_e32 v220, v134
	v_mov_b32_e32 v221, v135

; __device__ __forceinline__ unsigned cvt_pk_bf16(float lo, float hi) { unsigned r; asm volatile("v_cvt_pk_bf16_f32 %0, %1, %2" : "=v"(r) : "v"(lo), "v"(hi)); return r; }
;     __device__ __forceinline__ void operator()(const f32x4 (&acc)[2][2][4][2], const Unit& u, int wr, int wc, int fr, int fq) const {
;     ...
;             for (int m = 0; m < 4; ++m) rs[ai][m] = __builtin_amdgcn_rsqf((float)ss[u.pm * BM + ai * HALF + wr * 64 + m * 16 + fr] * (1.f / (2048.f * 262144.f)) + 1e-6f);
; #pragma unroll
;         for (int n = 0; n < 2; ++n) {
;             const int cbase = 128 * u.pn + 32 * wc + 16 * n + 4 * fq;
;             const f32x4 w0 = *(const f32x4*)(cw + cbase), w1 = *(const f32x4*)(cw + FF + cbase), w2 = *(const f32x4*)(cw + 2 * FF + cbase), b4 = *(const f32x4*)(cb + cbase);
; #pragma unroll
;             for (int ai = 0; ai < 2; ++ai) {
;                 const int slab = u.pm * 4 + 2 * ai + wr;
;                 f32x4 r1p = (f32x4){0.f, 0.f, 0.f, 0.f}, r2p = (f32x4){0.f, 0.f, 0.f, 0.f};
; #pragma unroll
;                 for (int m = 0; m < 4; ++m) {
;                     const f32x4 g = acc[ai][1][m][n] * rs[ai][m], v = acc[ai][0][m][n] * rs[ai][m];
;                     f32x4 r1, r2, a;
; #pragma unroll
;                     for (int e = 0; e < 4; ++e) { r1[e] = __shfl(g[e], src1); r2[e] = __shfl(g[e], src2); }
; #pragma unroll
;                     for (int e = 0; e < 4; ++e) {
;                         const float p1 = fr >= 1 ? r1[e] : r1p[e], p2 = fr >= 2 ? r2[e] : r2p[e];
;                         const float gg = b4[e] + w0[e] * p2 + w1[e] * p1 + w2[e] * g[e];
;                         a[e] = gg * __builtin_amdgcn_rcpf(1.f + __expf(-gg)) * v[e];
;                     }
;                     r1p = r1; r2p = r2;
;                     const size_t row = (size_t)(u.pm * BM + ai * HALF + wr * 64 + m * 16 + fr);
;                     if (m == 0 && fr < 2) {
;                         *(f32x4*)(GF + (size_t)(slab * 2 + fr) * FF + cbase) = g; *(f32x4*)(VF + (size_t)(slab * 2 + fr) * FF + cbase) = v;
;                     } else {
;                         typedef unsigned u32x2v __attribute__((ext_vector_type(2)));
;                         u32x2v w; w.x = cvt_pk_bf16(a[0], a[1]); w.y = cvt_pk_bf16(a[2], a[3]);
;                         *(u32x2v*)(ACT + row * FF + cbase) = w;
.LBB0_45:
	s_or_b64 exec, exec, s[10:11]
	s_nop 0
	v_ffbh_u32_e32 v134, v191
	v_min_u32_e32 v136, 32, v134
	v_lshlrev_b64 v[134:135], v136, v[190:191]
	v_min_u32_e32 v134, 1, v134
	v_or_b32_e32 v134, v135, v134
	v_cvt_f32_u32_e32 v134, v134
	v_ffbh_u32_e32 v135, v189
	v_sub_u32_e32 v136, 32, v136
	v_min_u32_e32 v143, 32, v135
	v_ldexp_f32 v134, v134, v136
	v_fmamk_f32 v136, v134, 0x31000000, v232
	v_lshlrev_b64 v[134:135], v143, v[188:189]
	v_min_u32_e32 v134, 1, v134
	v_or_b32_e32 v134, v135, v134
	v_cvt_f32_u32_e32 v134, v134
	v_sub_u32_e32 v135, 32, v143
	v_rsq_f32_e32 v142, v136
	v_mov_b32_e32 v149, v141
	v_ldexp_f32 v134, v134, v135
	v_fmamk_f32 v136, v134, 0x31000000, v232
	v_ffbh_u32_e32 v134, v187
	v_min_u32_e32 v143, 32, v134
	v_lshlrev_b64 v[134:135], v143, v[186:187]
	v_min_u32_e32 v134, 1, v134
	v_or_b32_e32 v134, v135, v134
	v_cvt_f32_u32_e32 v134, v134
	v_sub_u32_e32 v143, 32, v143
	s_movk_i32 s10, 0x5600
	v_rsq_f32_e32 v136, v136
	v_ldexp_f32 v134, v134, v143
	v_add_u32_e32 v143, s12, v197
	v_pk_mul_f32 v[128:129], v[128:129], v[142:143] op_sel_hi:[1,0]
	ds_bpermute_b32 v186, v161, v129
	ds_bpermute_b32 v191, v200, v129
	v_mov_b32_e32 v148, v129
	v_pk_mul_f32 v[126:127], v[126:127], v[142:143] op_sel_hi:[1,0]
	v_mad_i64_i32 v[146:147], s[10:11], v143, s10, 0
	s_waitcnt lgkmcnt(1)
	v_cndmask_b32_e64 v185, v186, v185, s[40:41]
	s_waitcnt lgkmcnt(0)
	v_cndmask_b32_e64 v129, v203, v191, s[42:43]
	v_pk_mul_f32 v[148:149], v[148:149], v[184:185]
	v_fma_f32 v129, v117, v129, v121
	v_add_f32_e32 v129, v149, v129
	v_add_f32_e32 v148, v148, v129
	v_mul_f32_e32 v129, 0xbfb8aa3b, v148
	v_exp_f32_e32 v129, v129
	ds_bpermute_b32 v149, v161, v128
	ds_bpermute_b32 v203, v200, v128
	ds_bpermute_b32 v143, v161, v126
	v_add_f32_e32 v129, 1.0, v129
	v_rcp_f32_e32 v185, v129
	s_waitcnt lgkmcnt(2)
	v_cndmask_b32_e64 v183, v149, v183, s[40:41]
	v_mov_b32_e32 v129, v140
	v_pk_mul_f32 v[128:129], v[128:129], v[182:183]
	s_waitcnt lgkmcnt(1)
	v_cndmask_b32_e64 v183, v202, v203, s[42:43]
	v_fma_f32 v183, v116, v183, v120
	v_add_f32_e32 v129, v129, v183
	v_add_f32_e32 v183, v128, v129
	v_mul_f32_e32 v128, 0xbfb8aa3b, v183
	ds_bpermute_b32 v189, v161, v127
	ds_bpermute_b32 v190, v200, v127
	v_exp_f32_e32 v128, v128
	s_waitcnt lgkmcnt(2)
	v_pk_mul_f32 v[124:125], v[124:125], v[142:143] op_sel_hi:[1,0]
	v_mul_f32_e32 v129, v148, v185
	ds_bpermute_b32 v187, v200, v126
	v_add_f32_e32 v128, 1.0, v128
	v_mul_f32_e32 v125, v125, v129
	v_rcp_f32_e32 v148, v128
	s_waitcnt lgkmcnt(2)
	v_cndmask_b32_e64 v181, v189, v181, s[40:41]
	v_mov_b32_e32 v128, v127
	v_mov_b32_e32 v129, v139
	s_waitcnt lgkmcnt(1)
	v_cndmask_b32_e64 v127, v201, v190, s[42:43]
	v_pk_mul_f32 v[128:129], v[128:129], v[180:181]
	v_fma_f32 v127, v115, v127, v119
	v_add_f32_e32 v127, v129, v127
	v_add_f32_e32 v128, v128, v127
	v_mul_f32_e32 v127, 0xbfb8aa3b, v128
	v_exp_f32_e32 v129, v127
	v_cndmask_b32_e64 v179, v143, v179, s[40:41]
	v_mov_b32_e32 v127, v138
	s_waitcnt lgkmcnt(0)
	v_cndmask_b32_e64 v163, v163, v187, s[42:43]
	v_pk_mul_f32 v[126:127], v[126:127], v[178:179]
	v_fma_f32 v163, v114, v163, v118
	v_add_f32_e32 v127, v127, v163
	v_add_f32_e32 v126, v126, v127
	v_mul_f32_e32 v127, 0xbfb8aa3b, v126
	v_exp_f32_e32 v127, v127
	v_add_f32_e32 v129, 1.0, v129
	v_rcp_f32_e32 v129, v129
	v_or_b32_e32 v137, 16, v160
	v_add_f32_e32 v127, 1.0, v127
	v_rcp_f32_e32 v127, v127
	v_mul_f32_e32 v148, v183, v148
	v_pk_mul_f32 v[112:113], v[112:113], v[136:137] op_sel_hi:[1,0]
	v_mul_f32_e32 v124, v124, v148
	ds_bpermute_b32 v148, v161, v113
	ds_bpermute_b32 v204, v200, v113
	v_pk_mul_f32 v[122:123], v[122:123], v[142:143] op_sel_hi:[1,0]
	v_mul_f32_e32 v128, v128, v129
	v_mul_f32_e32 v126, v126, v127
	v_mul_f32_e32 v123, v123, v128
	v_mul_f32_e32 v122, v122, v126
	v_mov_b64_e32 v[128:129], s[48:49]
	v_cvt_pk_bf16_f32 v126, v122, v123
	v_cvt_pk_bf16_f32 v127, v124, v125
	v_mad_i64_i32 v[122:123], s[10:11], v137, s17, v[128:129]
	v_lshlrev_b64 v[124:125], 1, v[156:157]
	v_lshl_add_u64 v[122:123], v[122:123], 0, v[124:125]
	v_mov_b32_e32 v206, v126
	v_mov_b32_e32 v207, v127
	s_waitcnt lgkmcnt(1)
	v_cndmask_b32_e64 v185, v148, v186, s[40:41]
	v_mov_b32_e32 v126, v113
	v_mov_b32_e32 v127, v141
	s_waitcnt lgkmcnt(0)
	v_cndmask_b32_e64 v113, v191, v204, s[42:43]
	v_pk_mul_f32 v[126:127], v[126:127], v[184:185]
	v_fma_f32 v113, v117, v113, v121
	v_add_f32_e32 v113, v127, v113
	v_add_f32_e32 v126, v126, v113
	v_mul_f32_e32 v113, 0xbfb8aa3b, v126
	v_exp_f32_e32 v113, v113
	ds_bpermute_b32 v127, v161, v112
	ds_bpermute_b32 v186, v200, v112
	v_pk_mul_f32 v[110:111], v[110:111], v[136:137] op_sel_hi:[1,0]
	v_add_f32_e32 v113, 1.0, v113
	v_rcp_f32_e32 v179, v113
	s_waitcnt lgkmcnt(1)
	v_cndmask_b32_e64 v183, v127, v149, s[40:41]
	v_mov_b32_e32 v113, v140
	s_waitcnt lgkmcnt(0)
	v_cndmask_b32_e64 v149, v203, v186, s[42:43]
	v_pk_mul_f32 v[112:113], v[112:113], v[182:183]
	v_fma_f32 v149, v116, v149, v120
	v_add_f32_e32 v113, v113, v149
	v_add_f32_e32 v149, v112, v113
	ds_bpermute_b32 v137, v161, v110
	v_mul_f32_e32 v112, 0xbfb8aa3b, v149
	ds_bpermute_b32 v201, v161, v111
	ds_bpermute_b32 v202, v200, v111
	v_exp_f32_e32 v112, v112
	s_waitcnt lgkmcnt(2)
	v_pk_mul_f32 v[108:109], v[108:109], v[136:137] op_sel_hi:[1,0]
	v_mul_f32_e32 v113, v126, v179
	ds_bpermute_b32 v163, v200, v110
	v_add_f32_e32 v112, 1.0, v112
	v_mul_f32_e32 v109, v109, v113
	v_rcp_f32_e32 v126, v112
	s_waitcnt lgkmcnt(2)
	v_cndmask_b32_e64 v181, v201, v189, s[40:41]
	v_mov_b32_e32 v112, v111
	v_mov_b32_e32 v113, v139
	s_waitcnt lgkmcnt(1)
; __device__ __forceinline__ unsigned cvt_pk_bf16(float lo, float hi) { unsigned r; asm volatile("v_cvt_pk_bf16_f32 %0, %1, %2" : "=v"(r) : "v"(lo), "v"(hi)); return r; }
;     __device__ __forceinline__ void operator()(const f32x4 (&acc)[2][2][4][2], const Unit& u, int wr, int wc, int fr, int fq) const {
;     ...
;                 for (int m = 0; m < 4; ++m) {
;                     const f32x4 g = acc[ai][1][m][n] * rs[ai][m], v = acc[ai][0][m][n] * rs[ai][m];
;                     f32x4 r1, r2, a;
; #pragma unroll
;                     for (int e = 0; e < 4; ++e) { r1[e] = __shfl(g[e], src1); r2[e] = __shfl(g[e], src2); }
; #pragma unroll
;                     for (int e = 0; e < 4; ++e) {
;                         const float p1 = fr >= 1 ? r1[e] : r1p[e], p2 = fr >= 2 ? r2[e] : r2p[e];
;                         const float gg = b4[e] + w0[e] * p2 + w1[e] * p1 + w2[e] * g[e];
;                         a[e] = gg * __builtin_amdgcn_rcpf(1.f + __expf(-gg)) * v[e];
;                     }
;                     r1p = r1; r2p = r2;
;                     const size_t row = (size_t)(u.pm * BM + ai * HALF + wr * 64 + m * 16 + fr);
;                     if (m == 0 && fr < 2) {
;                         *(f32x4*)(GF + (size_t)(slab * 2 + fr) * FF + cbase) = g; *(f32x4*)(VF + (size_t)(slab * 2 + fr) * FF + cbase) = v;
;                     } else {
;                         typedef unsigned u32x2v __attribute__((ext_vector_type(2)));
;                         u32x2v w; w.x = cvt_pk_bf16(a[0], a[1]); w.y = cvt_pk_bf16(a[2], a[3]);
;                         *(u32x2v*)(ACT + row * FF + cbase) = w;
;                     }
;                     if (m == 3 && fr >= 14) *(f32x4*)(GL + (size_t)(slab * 2 + fr - 14) * FF + cbase) = g;
	v_cndmask_b32_e64 v111, v190, v202, s[42:43]
	v_pk_mul_f32 v[112:113], v[112:113], v[180:181]
	v_fma_f32 v111, v115, v111, v119
	v_add_f32_e32 v111, v113, v111
	v_add_f32_e32 v112, v112, v111
	v_mul_f32_e32 v111, 0xbfb8aa3b, v112
	v_exp_f32_e32 v113, v111
	v_cndmask_b32_e64 v179, v137, v143, s[40:41]
	v_mov_b32_e32 v111, v138
	s_waitcnt lgkmcnt(0)
	v_cndmask_b32_e64 v143, v187, v163, s[42:43]
	v_pk_mul_f32 v[110:111], v[110:111], v[178:179]
	v_fma_f32 v143, v114, v143, v118
	v_add_f32_e32 v111, v111, v143
	v_add_f32_e32 v110, v110, v111
	v_mul_f32_e32 v111, 0xbfb8aa3b, v110
	v_exp_f32_e32 v111, v111
	v_add_f32_e32 v113, 1.0, v113
	v_rcp_f32_e32 v113, v113
	v_fmamk_f32 v134, v134, 0x31000000, v232
	v_add_f32_e32 v111, 1.0, v111
	v_rcp_f32_e32 v111, v111
	v_rsq_f32_e32 v134, v134
	v_pk_mul_f32 v[106:107], v[106:107], v[136:137] op_sel_hi:[1,0]
	v_mul_f32_e32 v126, v149, v126
	v_mul_f32_e32 v112, v112, v113
	v_mul_f32_e32 v110, v110, v111
	v_or_b32_e32 v188, 32, v160
	v_mul_f32_e32 v108, v108, v126
	v_mul_f32_e32 v107, v107, v112
	v_mul_f32_e32 v106, v106, v110
	v_or_b32_e32 v135, 48, v160
	v_cvt_pk_bf16_f32 v106, v106, v107
	v_cvt_pk_bf16_f32 v107, v108, v109
	v_mad_i64_i32 v[108:109], s[10:11], v188, s17, v[128:129]
	v_lshl_add_u64 v[108:109], v[108:109], 0, v[124:125]
	v_pk_mul_f32 v[104:105], v[104:105], v[134:135] op_sel_hi:[1,0]
	v_mov_b32_e32 v208, v106
	v_mov_b32_e32 v209, v107
	ds_bpermute_b32 v106, v161, v105
	ds_bpermute_b32 v126, v200, v105
	v_mov_b32_e32 v107, v141
	ds_bpermute_b32 v143, v200, v104
	v_pk_mul_f32 v[102:103], v[102:103], v[134:135] op_sel_hi:[1,0]
	s_waitcnt lgkmcnt(2)
	v_cndmask_b32_e64 v185, v106, v148, s[40:41]
	v_mov_b32_e32 v106, v105
	s_waitcnt lgkmcnt(1)
	v_cndmask_b32_e64 v126, v204, v126, s[42:43]
	v_pk_mul_f32 v[106:107], v[106:107], v[184:185]
	v_fma_f32 v126, v117, v126, v121
	v_add_f32_e32 v107, v107, v126
	v_add_f32_e32 v126, v106, v107
	v_mul_f32_e32 v106, 0xbfb8aa3b, v126
	v_exp_f32_e32 v106, v106
	ds_bpermute_b32 v107, v161, v104
	ds_bpermute_b32 v112, v161, v103
	ds_bpermute_b32 v113, v200, v103
	v_add_f32_e32 v106, 1.0, v106
	v_rcp_f32_e32 v148, v106
	s_waitcnt lgkmcnt(2)
	v_cndmask_b32_e64 v183, v107, v127, s[40:41]
	v_mov_b32_e32 v106, v104
	v_mov_b32_e32 v107, v140
	v_cndmask_b32_e64 v127, v186, v143, s[42:43]
	v_pk_mul_f32 v[106:107], v[106:107], v[182:183]
	v_fma_f32 v127, v116, v127, v120
	v_add_f32_e32 v107, v107, v127
	v_add_f32_e32 v127, v106, v107
	v_mul_f32_e32 v106, 0xbfb8aa3b, v127
	v_exp_f32_e32 v106, v106
	v_pk_mul_f32 v[100:101], v[100:101], v[134:135] op_sel_hi:[1,0]
	v_mul_f32_e32 v107, v126, v148
	ds_bpermute_b32 v110, v161, v102
	v_add_f32_e32 v106, 1.0, v106
	ds_bpermute_b32 v111, v200, v102
	v_mul_f32_e32 v101, v101, v107
	v_rcp_f32_e32 v126, v106
	s_waitcnt lgkmcnt(3)
	v_cndmask_b32_e64 v181, v112, v201, s[40:41]
	v_mov_b32_e32 v106, v103
	v_mov_b32_e32 v107, v139
	s_waitcnt lgkmcnt(2)
	v_cndmask_b32_e64 v112, v202, v113, s[42:43]
	v_pk_mul_f32 v[106:107], v[106:107], v[180:181]
	v_fma_f32 v112, v115, v112, v119
	v_add_f32_e32 v107, v107, v112
	v_add_f32_e32 v112, v106, v107
	v_mul_f32_e32 v106, 0xbfb8aa3b, v112
	v_exp_f32_e32 v113, v106
	s_waitcnt lgkmcnt(1)
	v_cndmask_b32_e64 v179, v110, v137, s[40:41]
	v_mov_b32_e32 v106, v102
	v_mov_b32_e32 v107, v138
	s_waitcnt lgkmcnt(0)
	v_cndmask_b32_e64 v110, v163, v111, s[42:43]
	v_pk_mul_f32 v[106:107], v[106:107], v[178:179]
	v_fma_f32 v110, v114, v110, v118
	v_add_f32_e32 v107, v107, v110
	v_add_f32_e32 v106, v106, v107
	v_mul_f32_e32 v107, 0xbfb8aa3b, v106
	v_exp_f32_e32 v107, v107
	v_add_f32_e32 v111, 1.0, v113
	v_rcp_f32_e32 v111, v111
	v_mul_f32_e32 v110, v127, v126
	v_add_f32_e32 v107, 1.0, v107
	v_rcp_f32_e32 v107, v107
	v_pk_mul_f32 v[98:99], v[98:99], v[134:135] op_sel_hi:[1,0]
	v_mul_f32_e32 v100, v100, v110
	v_mul_f32_e32 v110, v112, v111
	v_mul_f32_e32 v106, v106, v107
	v_mul_f32_e32 v99, v99, v110
	v_mul_f32_e32 v98, v98, v106
	v_cvt_pk_bf16_f32 v98, v98, v99
	v_cvt_pk_bf16_f32 v99, v100, v101
	v_mad_i64_i32 v[100:101], s[10:11], v135, s17, v[128:129]
	v_readlane_b32 s10, v254, 44
	v_lshl_add_u64 v[110:111], v[100:101], 0, v[124:125]
	v_readlane_b32 s11, v254, 45
	v_mov_b32_e32 v210, v98
	v_mov_b32_e32 v211, v99
	s_nop 0
	v_lshl_add_u64 v[98:99], s[10:11], 0, v[146:147]
	v_lshl_add_u64 v[106:107], v[156:157], 2, v[98:99]
	s_and_saveexec_b64 s[10:11], s[44:45]
	v_readlane_b32 s85, v254, 57
	v_readlane_b32 s93, v254, 58
	s_cbranch_execz .LBB0_47
	global_store_dwordx4 v[106:107], v[102:105], off
; __device__ __forceinline__ unsigned cvt_pk_bf16(float lo, float hi) { unsigned r; asm volatile("v_cvt_pk_bf16_f32 %0, %1, %2" : "=v"(r) : "v"(lo), "v"(hi)); return r; }
;     __device__ __forceinline__ void operator()(const f32x4 (&acc)[2][2][4][2], const Unit& u, int wr, int wc, int fr, int fq) const {
;     ...
;             for (int m = 0; m < 4; ++m) rs[ai][m] = __builtin_amdgcn_rsqf((float)ss[u.pm * BM + ai * HALF + wr * 64 + m * 16 + fr] * (1.f / (2048.f * 262144.f)) + 1e-6f);
; #pragma unroll
;         for (int n = 0; n < 2; ++n) {
;             const int cbase = 128 * u.pn + 32 * wc + 16 * n + 4 * fq;
;             const f32x4 w0 = *(const f32x4*)(cw + cbase), w1 = *(const f32x4*)(cw + FF + cbase), w2 = *(const f32x4*)(cw + 2 * FF + cbase), b4 = *(const f32x4*)(cb + cbase);
; #pragma unroll
;             for (int ai = 0; ai < 2; ++ai) {
;                 const int slab = u.pm * 4 + 2 * ai + wr;
;                 f32x4 r1p = (f32x4){0.f, 0.f, 0.f, 0.f}, r2p = (f32x4){0.f, 0.f, 0.f, 0.f};
; #pragma unroll
;                 for (int m = 0; m < 4; ++m) {
;                     const f32x4 g = acc[ai][1][m][n] * rs[ai][m], v = acc[ai][0][m][n] * rs[ai][m];
;                     f32x4 r1, r2, a;
; #pragma unroll
;                     for (int e = 0; e < 4; ++e) { r1[e] = __shfl(g[e], src1); r2[e] = __shfl(g[e], src2); }
; #pragma unroll
;                     for (int e = 0; e < 4; ++e) {
;                         const float p1 = fr >= 1 ? r1[e] : r1p[e], p2 = fr >= 2 ? r2[e] : r2p[e];
;                         const float gg = b4[e] + w0[e] * p2 + w1[e] * p1 + w2[e] * g[e];
;                         a[e] = gg * __builtin_amdgcn_rcpf(1.f + __expf(-gg)) * v[e];
;                     }
;                     r1p = r1; r2p = r2;
;                     const size_t row = (size_t)(u.pm * BM + ai * HALF + wr * 64 + m * 16 + fr);
;                     if (m == 0 && fr < 2) {
;                         *(f32x4*)(GF + (size_t)(slab * 2 + fr) * FF + cbase) = g; *(f32x4*)(VF + (size_t)(slab * 2 + fr) * FF + cbase) = v;
;                     } else {
;                         typedef unsigned u32x2v __attribute__((ext_vector_type(2)));
;                         u32x2v w; w.x = cvt_pk_bf16(a[0], a[1]); w.y = cvt_pk_bf16(a[2], a[3]);
;                         *(u32x2v*)(ACT + row * FF + cbase) = w;
.LBB0_47:
	s_or_b64 exec, exec, s[10:11]
	v_ffbh_u32_e32 v98, v177
	v_min_u32_e32 v100, 32, v98
	v_lshlrev_b64 v[98:99], v100, v[176:177]
	v_min_u32_e32 v98, 1, v98
	v_or_b32_e32 v98, v99, v98
	v_cvt_f32_u32_e32 v98, v98
	v_sub_u32_e32 v99, 32, v100
	v_add_u32_e32 v180, 0x80, v160
	v_mov_b32_e32 v146, v130
	v_ldexp_f32 v98, v98, v99
	v_fmamk_f32 v98, v98, 0x31000000, v232
	v_rsq_f32_e32 v102, v98
	v_mov_b32_e32 v147, v138
	v_mov_b32_e32 v128, v131
	v_mov_b32_e32 v129, v139
	v_pk_mul_f32 v[98:99], v[90:91], v[102:103] op_sel_hi:[1,0]
	v_pk_mul_f32 v[100:101], v[92:93], v[102:103] op_sel_hi:[1,0]
	ds_bpermute_b32 v103, v200, v98
	ds_bpermute_b32 v135, v161, v98
	ds_bpermute_b32 v177, v161, v99
	ds_bpermute_b32 v137, v200, v99
	ds_bpermute_b32 v163, v161, v100
	ds_bpermute_b32 v143, v200, v100
	ds_bpermute_b32 v179, v161, v101
	ds_bpermute_b32 v181, v200, v101
	s_waitcnt lgkmcnt(7)
	v_pk_mul_f32 v[92:93], v[96:97], v[102:103] op_sel_hi:[1,0]
	v_pk_mul_f32 v[90:91], v[94:95], v[102:103] op_sel_hi:[1,0]
	v_mov_b32_e32 v148, v132
	v_mov_b32_e32 v149, v140
	v_mov_b32_e32 v126, v133
	v_mov_b32_e32 v127, v141
	s_and_saveexec_b64 s[10:11], s[42:43]
	s_xor_b64 s[10:11], exec, s[10:11]
	s_cbranch_execz .LBB0_49
	v_mov_b32_e32 v126, v133
	v_mov_b32_e32 v127, v141
	v_mov_b32_e32 v178, v101
	s_waitcnt lgkmcnt(1)
	v_pk_mul_f32 v[94:95], v[126:127], v[178:179]
	s_waitcnt lgkmcnt(0)
	v_fma_f32 v96, v117, v181, v121
	v_add_f32_e32 v95, v95, v96
	v_add_f32_e32 v94, v94, v95
	v_mul_f32_e32 v95, 0xbfb8aa3b, v94
	v_exp_f32_e32 v95, v95
	v_mov_b32_e32 v133, v140
	v_mov_b32_e32 v101, v163
	v_mov_b32_e32 v128, v131
	v_add_f32_e32 v95, 1.0, v95
	v_rcp_f32_e32 v95, v95
	v_mov_b32_e32 v129, v139
	v_mov_b32_e32 v176, v99
	v_mov_b32_e32 v131, v138
	v_mul_f32_e32 v94, v94, v95
	v_mul_f32_e32 v96, v93, v94
	v_pk_mul_f32 v[94:95], v[132:133], v[100:101]
	v_fma_f32 v93, v116, v143, v120
	v_add_f32_e32 v93, v95, v93
	v_add_f32_e32 v93, v94, v93
	v_mul_f32_e32 v94, 0xbfb8aa3b, v93
	v_exp_f32_e32 v94, v94
	v_fma_f32 v95, v115, v137, v119
	v_mov_b32_e32 v99, v135
	v_mov_b64_e32 v[148:149], v[132:133]
	v_add_f32_e32 v94, 1.0, v94
	v_rcp_f32_e32 v94, v94
	v_mov_b64_e32 v[146:147], v[130:131]
	v_mul_f32_e32 v93, v93, v94
	v_mul_f32_e32 v94, v92, v93
	v_pk_mul_f32 v[92:93], v[128:129], v[176:177]
	s_nop 0
	v_add_f32_e32 v93, v93, v95
	v_add_f32_e32 v92, v92, v93
	v_mul_f32_e32 v93, 0xbfb8aa3b, v92
	v_exp_f32_e32 v93, v93
	v_fma_f32 v95, v114, v103, v118
	v_add_f32_e32 v93, 1.0, v93
	v_rcp_f32_e32 v93, v93
	s_nop 0
	v_mul_f32_e32 v92, v92, v93
	v_mul_f32_e32 v91, v91, v92
	v_pk_mul_f32 v[92:93], v[130:131], v[98:99]
	s_nop 0
	v_add_f32_e32 v93, v93, v95
	v_add_f32_e32 v92, v92, v93
	v_mul_f32_e32 v93, 0xbfb8aa3b, v92
	v_exp_f32_e32 v93, v93
	s_nop 0
	v_add_f32_e32 v93, 1.0, v93
	v_rcp_f32_e32 v93, v93
	s_nop 0
	v_mul_f32_e32 v92, v92, v93
	v_mul_f32_e32 v90, v90, v92
	v_mov_b64_e32 v[92:93], s[48:49]
	v_mad_i64_i32 v[92:93], s[68:69], v180, s17, v[92:93]
	v_cvt_pk_bf16_f32 v90, v90, v91
	v_cvt_pk_bf16_f32 v91, v94, v96
	v_lshl_add_u64 v[92:93], v[156:157], 1, v[92:93]
	v_mov_b32_e32 v212, v90
	v_mov_b32_e32 v213, v91

; __device__ __forceinline__ unsigned cvt_pk_bf16(float lo, float hi) { unsigned r; asm volatile("v_cvt_pk_bf16_f32 %0, %1, %2" : "=v"(r) : "v"(lo), "v"(hi)); return r; }
;     __device__ __forceinline__ void operator()(const f32x4 (&acc)[2][2][4][2], const Unit& u, int wr, int wc, int fr, int fq) const {
;     ...
;         for (int n = 0; n < 2; ++n) {
;             const int cbase = 128 * u.pn + 32 * wc + 16 * n + 4 * fq;
;             const f32x4 w0 = *(const f32x4*)(cw + cbase), w1 = *(const f32x4*)(cw + FF + cbase), w2 = *(const f32x4*)(cw + 2 * FF + cbase), b4 = *(const f32x4*)(cb + cbase);
; #pragma unroll
;             for (int ai = 0; ai < 2; ++ai) {
;                 const int slab = u.pm * 4 + 2 * ai + wr;
;                 f32x4 r1p = (f32x4){0.f, 0.f, 0.f, 0.f}, r2p = (f32x4){0.f, 0.f, 0.f, 0.f};
; #pragma unroll
;                 for (int m = 0; m < 4; ++m) {
;                     const f32x4 g = acc[ai][1][m][n] * rs[ai][m], v = acc[ai][0][m][n] * rs[ai][m];
;                     f32x4 r1, r2, a;
; #pragma unroll
;                     for (int e = 0; e < 4; ++e) { r1[e] = __shfl(g[e], src1); r2[e] = __shfl(g[e], src2); }
; #pragma unroll
;                     for (int e = 0; e < 4; ++e) {
;                         const float p1 = fr >= 1 ? r1[e] : r1p[e], p2 = fr >= 2 ? r2[e] : r2p[e];
;                         const float gg = b4[e] + w0[e] * p2 + w1[e] * p1 + w2[e] * g[e];
;                         a[e] = gg * __builtin_amdgcn_rcpf(1.f + __expf(-gg)) * v[e];
;                     }
;                     r1p = r1; r2p = r2;
;                     const size_t row = (size_t)(u.pm * BM + ai * HALF + wr * 64 + m * 16 + fr);
;                     if (m == 0 && fr < 2) {
;                         *(f32x4*)(GF + (size_t)(slab * 2 + fr) * FF + cbase) = g; *(f32x4*)(VF + (size_t)(slab * 2 + fr) * FF + cbase) = v;
;                     } else {
;                         typedef unsigned u32x2v __attribute__((ext_vector_type(2)));
;                         u32x2v w; w.x = cvt_pk_bf16(a[0], a[1]); w.y = cvt_pk_bf16(a[2], a[3]);
;                         *(u32x2v*)(ACT + row * FF + cbase) = w;
.LBB0_53:
	s_or_b64 exec, exec, s[10:11]
	s_nop 0
	v_or_b32_e32 v70, 16, v156
	v_ashrrev_i32_e32 v71, 31, v70
	v_lshlrev_b64 v[70:71], 2, v[70:71]
	v_lshl_add_u64 v[72:73], s[60:61], 0, v[70:71]
	v_lshl_add_u64 v[70:71], s[62:63], 0, v[70:71]
	global_load_dwordx4 v[66:69], v[166:167], off offset:64
	global_load_dwordx4 v[78:81], v[72:73], off
	global_load_dwordx4 v[74:77], v[70:71], off
	s_nop 0
	global_load_dwordx4 v[70:73], v[164:165], off offset:64
	v_mov_b32_e32 v163, v162
	v_mov_b32_e32 v120, v162
	v_mov_b32_e32 v121, v162
	v_pk_mul_f32 v[84:85], v[60:61], v[120:121]
	v_pk_mul_f32 v[82:83], v[58:59], v[162:163]
	ds_bpermute_b32 v101, v161, v82
	ds_bpermute_b32 v91, v200, v82
	ds_bpermute_b32 v115, v161, v83
	ds_bpermute_b32 v93, v200, v83
	ds_bpermute_b32 v117, v161, v84
	ds_bpermute_b32 v95, v200, v84
	ds_bpermute_b32 v119, v161, v85
	ds_bpermute_b32 v103, v200, v85
	v_pk_mul_f32 v[60:61], v[64:65], v[120:121]
	v_pk_mul_f32 v[58:59], v[62:63], v[162:163]
	s_and_saveexec_b64 s[10:11], s[42:43]
	s_xor_b64 s[10:11], exec, s[10:11]
	s_cbranch_execz .LBB0_55
	v_mov_b32_e32 v62, v85
	s_waitcnt vmcnt(2)
	v_mov_b32_e32 v63, v81
	s_waitcnt vmcnt(1)
	v_mov_b32_e32 v118, v77
	s_waitcnt lgkmcnt(1)
	v_pk_mul_f32 v[62:63], v[62:63], v[118:119]
	s_waitcnt vmcnt(0) lgkmcnt(0)
	v_fma_f32 v64, v69, v103, v73
	v_add_f32_e32 v63, v63, v64
	v_add_f32_e32 v62, v62, v63
	v_mul_f32_e32 v63, 0xbfb8aa3b, v62
	v_exp_f32_e32 v63, v63
	v_mov_b32_e32 v85, v80
	v_mov_b32_e32 v116, v76
	v_mov_b32_e32 v114, v75
	v_add_f32_e32 v63, 1.0, v63
	v_rcp_f32_e32 v63, v63
	v_mov_b32_e32 v100, v74
	v_mul_f32_e32 v62, v62, v63
	v_mul_f32_e32 v64, v61, v62
	v_pk_mul_f32 v[62:63], v[84:85], v[116:117]
	v_fma_f32 v61, v68, v95, v72
	v_add_f32_e32 v61, v63, v61
	v_add_f32_e32 v61, v62, v61
	v_mul_f32_e32 v62, 0xbfb8aa3b, v61
	v_exp_f32_e32 v62, v62
	v_fma_f32 v63, v67, v93, v71
	v_add_f32_e32 v62, 1.0, v62
	v_rcp_f32_e32 v62, v62
	s_nop 0
	v_mul_f32_e32 v61, v61, v62
	v_mul_f32_e32 v62, v60, v61
	v_mov_b32_e32 v60, v83
	v_mov_b32_e32 v61, v79
	v_pk_mul_f32 v[60:61], v[60:61], v[114:115]
	v_mov_b32_e32 v83, v78
	v_add_f32_e32 v61, v61, v63
	v_add_f32_e32 v60, v60, v61
	v_mul_f32_e32 v61, 0xbfb8aa3b, v60
	v_exp_f32_e32 v61, v61
	v_fma_f32 v63, v66, v91, v70
	v_add_f32_e32 v61, 1.0, v61
	v_rcp_f32_e32 v61, v61
	s_nop 0
	v_mul_f32_e32 v60, v60, v61
	v_mul_f32_e32 v59, v59, v60
	v_pk_mul_f32 v[60:61], v[82:83], v[100:101]
	s_nop 0
	v_add_f32_e32 v61, v61, v63
	v_add_f32_e32 v60, v60, v61
	v_mul_f32_e32 v61, 0xbfb8aa3b, v60
	v_exp_f32_e32 v61, v61
	s_nop 0
	v_add_f32_e32 v61, 1.0, v61
	v_rcp_f32_e32 v61, v61
	s_nop 0
	v_mul_f32_e32 v60, v60, v61
	v_mul_f32_e32 v58, v58, v60
	v_mov_b64_e32 v[60:61], s[48:49]
	v_mad_i64_i32 v[60:61], s[12:13], v160, s17, v[60:61]
	v_cvt_pk_bf16_f32 v58, v58, v59
	v_cvt_pk_bf16_f32 v59, v62, v64
	v_lshl_add_u64 v[60:61], v[156:157], 1, v[60:61]
	v_mov_b32_e32 v64, v77
	v_mov_b32_e32 v62, v75
	s_nop 1
	v_permlane16_swap_b32_e32 v220, v58
	v_permlane16_swap_b32_e32 v221, v59
	v_mov_b32_e32 v222, v58
	v_mov_b32_e32 v223, v59
	v_add_co_u32_e64 v60, s[98:99], v60, v205
	s_nop 1
	v_addc_co_u32_e64 v61, s[98:99], 0, v61, s[98:99]
	global_store_dwordx4 v[60:61], v[220:223], off

; __device__ __forceinline__ unsigned cvt_pk_bf16(float lo, float hi) { unsigned r; asm volatile("v_cvt_pk_bf16_f32 %0, %1, %2" : "=v"(r) : "v"(lo), "v"(hi)); return r; }
;     __device__ __forceinline__ void operator()(const f32x4 (&acc)[2][2][4][2], const Unit& u, int wr, int wc, int fr, int fq) const {
;     ...
;                 for (int m = 0; m < 4; ++m) {
;                     const f32x4 g = acc[ai][1][m][n] * rs[ai][m], v = acc[ai][0][m][n] * rs[ai][m];
;                     f32x4 r1, r2, a;
; #pragma unroll
;                     for (int e = 0; e < 4; ++e) { r1[e] = __shfl(g[e], src1); r2[e] = __shfl(g[e], src2); }
; #pragma unroll
;                     for (int e = 0; e < 4; ++e) {
;                         const float p1 = fr >= 1 ? r1[e] : r1p[e], p2 = fr >= 2 ? r2[e] : r2p[e];
;                         const float gg = b4[e] + w0[e] * p2 + w1[e] * p1 + w2[e] * g[e];
;                         a[e] = gg * __builtin_amdgcn_rcpf(1.f + __expf(-gg)) * v[e];
;                     }
;                     r1p = r1; r2p = r2;
;                     const size_t row = (size_t)(u.pm * BM + ai * HALF + wr * 64 + m * 16 + fr);
;                     if (m == 0 && fr < 2) {
;                         *(f32x4*)(GF + (size_t)(slab * 2 + fr) * FF + cbase) = g; *(f32x4*)(VF + (size_t)(slab * 2 + fr) * FF + cbase) = v;
;                     } else {
;                         typedef unsigned u32x2v __attribute__((ext_vector_type(2)));
;                         u32x2v w; w.x = cvt_pk_bf16(a[0], a[1]); w.y = cvt_pk_bf16(a[2], a[3]);
;                         *(u32x2v*)(ACT + row * FF + cbase) = w;
;                     }
;                     if (m == 3 && fr >= 14) *(f32x4*)(GL + (size_t)(slab * 2 + fr - 14) * FF + cbase) = g;
.LBB0_57:
	s_or_b64 exec, exec, s[10:11]
	v_mov_b32_e32 v58, v142
	v_mov_b32_e32 v59, v142
	v_pk_mul_f32 v[56:57], v[56:57], v[58:59]
	ds_bpermute_b32 v83, v161, v57
	ds_bpermute_b32 v114, v200, v57
	v_mov_b32_e32 v60, v57
	s_waitcnt vmcnt(2)
	v_mov_b32_e32 v61, v81
	v_pk_mul_f32 v[52:53], v[52:53], v[58:59]
	s_waitcnt lgkmcnt(1)
	v_cndmask_b32_e64 v65, v83, v119, s[40:41]
	s_waitcnt lgkmcnt(0)
	v_cndmask_b32_e64 v57, v103, v114, s[42:43]
	v_pk_mul_f32 v[60:61], v[60:61], v[64:65]
	s_waitcnt vmcnt(0)
	v_fma_f32 v57, v69, v57, v73
	v_add_f32_e32 v57, v61, v57
	v_add_f32_e32 v60, v60, v57
	v_mul_f32_e32 v57, 0xbfb8aa3b, v60
	v_exp_f32_e32 v57, v57
	ds_bpermute_b32 v61, v161, v56
	ds_bpermute_b32 v103, v200, v56
	v_mov_b32_e32 v143, v142
	v_add_f32_e32 v57, 1.0, v57
	v_rcp_f32_e32 v58, v57
	s_waitcnt lgkmcnt(1)
	v_cndmask_b32_e64 v77, v61, v117, s[40:41]
	v_mov_b32_e32 v57, v80
	s_waitcnt lgkmcnt(0)
	v_cndmask_b32_e64 v59, v95, v103, s[42:43]
	v_pk_mul_f32 v[56:57], v[56:57], v[76:77]
	v_fma_f32 v59, v68, v59, v72
	v_add_f32_e32 v57, v57, v59
	v_add_f32_e32 v59, v56, v57
	v_pk_mul_f32 v[54:55], v[54:55], v[142:143]
	v_mul_f32_e32 v56, 0xbfb8aa3b, v59
	ds_bpermute_b32 v85, v161, v55
	ds_bpermute_b32 v100, v200, v55
	v_exp_f32_e32 v56, v56
	v_mul_f32_e32 v57, v60, v58
	ds_bpermute_b32 v82, v161, v54
	ds_bpermute_b32 v84, v200, v54
	v_add_f32_e32 v56, 1.0, v56
	v_mul_f32_e32 v53, v53, v57
	v_rcp_f32_e32 v58, v56
	s_waitcnt lgkmcnt(3)
	v_cndmask_b32_e64 v63, v85, v115, s[40:41]
	v_mov_b32_e32 v56, v55
	v_mov_b32_e32 v57, v79
	s_waitcnt lgkmcnt(2)
	v_cndmask_b32_e64 v55, v93, v100, s[42:43]
	v_pk_mul_f32 v[56:57], v[56:57], v[62:63]
	v_fma_f32 v55, v67, v55, v71
	v_add_f32_e32 v55, v57, v55
	v_add_f32_e32 v56, v56, v55
	v_mul_f32_e32 v55, 0xbfb8aa3b, v56
	v_exp_f32_e32 v57, v55
	s_waitcnt lgkmcnt(1)
	v_cndmask_b32_e64 v75, v82, v101, s[40:41]
	v_mov_b32_e32 v55, v78
	s_waitcnt lgkmcnt(0)
	v_cndmask_b32_e64 v60, v91, v84, s[42:43]
	v_pk_mul_f32 v[54:55], v[54:55], v[74:75]
	v_fma_f32 v60, v66, v60, v70
	v_add_f32_e32 v55, v55, v60
	v_add_f32_e32 v54, v54, v55
	v_mul_f32_e32 v55, 0xbfb8aa3b, v54
	v_exp_f32_e32 v55, v55
	v_add_f32_e32 v57, 1.0, v57
	v_rcp_f32_e32 v57, v57
	v_pk_mul_f32 v[50:51], v[50:51], v[142:143]
	v_add_f32_e32 v55, 1.0, v55
	v_rcp_f32_e32 v55, v55
	v_mul_f32_e32 v56, v56, v57
	v_mul_f32_e32 v58, v59, v58
	v_mul_f32_e32 v51, v51, v56
	v_mul_f32_e32 v54, v54, v55
	v_mul_f32_e32 v50, v50, v54
	v_mul_f32_e32 v52, v52, v58
	v_cvt_pk_bf16_f32 v50, v50, v51
	v_cvt_pk_bf16_f32 v51, v52, v53
	s_nop 1
	v_permlane16_swap_b32_e32 v206, v50
	v_permlane16_swap_b32_e32 v207, v51
	v_mov_b32_e32 v220, v206
	v_mov_b32_e32 v221, v207
	v_mov_b32_e32 v222, v50
	v_mov_b32_e32 v223, v51
	v_add_co_u32_e64 v122, s[98:99], v122, v205
	s_nop 1
	v_addc_co_u32_e64 v123, s[98:99], 0, v123, s[98:99]
	global_store_dwordx4 v[122:123], v[220:223], off
	v_mov_b32_e32 v50, v136
	v_mov_b32_e32 v51, v136
	v_pk_mul_f32 v[48:49], v[48:49], v[50:51]
	ds_bpermute_b32 v55, v161, v49
	ds_bpermute_b32 v59, v200, v49
	v_mov_b32_e32 v52, v49
	v_mov_b32_e32 v53, v81
	ds_bpermute_b32 v60, v200, v48
	s_waitcnt lgkmcnt(2)
	v_cndmask_b32_e64 v65, v55, v83, s[40:41]
	s_waitcnt lgkmcnt(1)
	v_cndmask_b32_e64 v49, v114, v59, s[42:43]
	v_pk_mul_f32 v[52:53], v[52:53], v[64:65]
	v_fma_f32 v49, v69, v49, v73
	v_add_f32_e32 v49, v53, v49
	v_add_f32_e32 v52, v52, v49
	v_mul_f32_e32 v49, 0xbfb8aa3b, v52
	v_exp_f32_e32 v49, v49
	ds_bpermute_b32 v53, v161, v48
	v_pk_mul_f32 v[44:45], v[44:45], v[50:51]
	s_waitcnt lgkmcnt(1)
	v_cndmask_b32_e64 v51, v103, v60, s[42:43]
	v_add_f32_e32 v49, 1.0, v49
	v_rcp_f32_e32 v50, v49
	s_waitcnt lgkmcnt(0)
	v_cndmask_b32_e64 v77, v53, v61, s[40:41]
	v_mov_b32_e32 v49, v80
	v_pk_mul_f32 v[48:49], v[48:49], v[76:77]
	v_fma_f32 v51, v68, v51, v72
	v_add_f32_e32 v49, v49, v51
	v_mov_b32_e32 v137, v136
	v_add_f32_e32 v51, v48, v49
	v_pk_mul_f32 v[46:47], v[46:47], v[136:137]
	v_mul_f32_e32 v48, 0xbfb8aa3b, v51
	ds_bpermute_b32 v57, v161, v47
	ds_bpermute_b32 v58, v200, v47
	v_exp_f32_e32 v48, v48
	v_mul_f32_e32 v49, v52, v50
	ds_bpermute_b32 v54, v161, v46
	ds_bpermute_b32 v56, v200, v46
	v_add_f32_e32 v48, 1.0, v48
	v_mul_f32_e32 v45, v45, v49
	v_rcp_f32_e32 v50, v48
	s_waitcnt lgkmcnt(3)
	v_cndmask_b32_e64 v63, v57, v85, s[40:41]
	v_mov_b32_e32 v48, v47
	v_mov_b32_e32 v49, v79
	s_waitcnt lgkmcnt(2)
	v_cndmask_b32_e64 v47, v100, v58, s[42:43]
	v_pk_mul_f32 v[48:49], v[48:49], v[62:63]
	v_fma_f32 v47, v67, v47, v71
	v_add_f32_e32 v47, v49, v47
	v_add_f32_e32 v48, v48, v47
	v_mul_f32_e32 v47, 0xbfb8aa3b, v48
	v_exp_f32_e32 v49, v47
	s_waitcnt lgkmcnt(1)
	v_cndmask_b32_e64 v75, v54, v82, s[40:41]
	v_mov_b32_e32 v47, v78
	s_waitcnt lgkmcnt(0)
	v_cndmask_b32_e64 v52, v84, v56, s[42:43]
	v_pk_mul_f32 v[46:47], v[46:47], v[74:75]
	v_fma_f32 v52, v66, v52, v70
	v_add_f32_e32 v47, v47, v52
	v_add_f32_e32 v46, v46, v47
	v_mul_f32_e32 v47, 0xbfb8aa3b, v46
	v_exp_f32_e32 v47, v47
	v_add_f32_e32 v49, 1.0, v49
	v_rcp_f32_e32 v49, v49
	v_pk_mul_f32 v[42:43], v[42:43], v[136:137]
	v_add_f32_e32 v47, 1.0, v47
	v_rcp_f32_e32 v47, v47
	v_mul_f32_e32 v48, v48, v49
	v_mul_f32_e32 v50, v51, v50
	v_mul_f32_e32 v43, v43, v48
	v_mul_f32_e32 v46, v46, v47
	v_mul_f32_e32 v42, v42, v46
	v_mul_f32_e32 v44, v44, v50
	v_cvt_pk_bf16_f32 v42, v42, v43
	v_cvt_pk_bf16_f32 v43, v44, v45
	s_nop 1
	v_permlane16_swap_b32_e32 v208, v42
	v_permlane16_swap_b32_e32 v209, v43
	v_mov_b32_e32 v220, v208
	v_mov_b32_e32 v221, v209
	v_mov_b32_e32 v222, v42
	v_mov_b32_e32 v223, v43
	v_add_co_u32_e64 v108, s[98:99], v108, v205
	s_nop 1
	v_addc_co_u32_e64 v109, s[98:99], 0, v109, s[98:99]
	global_store_dwordx4 v[108:109], v[220:223], off
	v_mov_b32_e32 v42, v134
	v_mov_b32_e32 v43, v134
	v_pk_mul_f32 v[40:41], v[40:41], v[42:43]
	ds_bpermute_b32 v44, v161, v41
	ds_bpermute_b32 v50, v200, v41
	v_mov_b32_e32 v45, v81
	ds_bpermute_b32 v51, v200, v40
	v_pk_mul_f32 v[36:37], v[36:37], v[42:43]
	s_waitcnt lgkmcnt(2)
; __device__ __forceinline__ unsigned cvt_pk_bf16(float lo, float hi) { unsigned r; asm volatile("v_cvt_pk_bf16_f32 %0, %1, %2" : "=v"(r) : "v"(lo), "v"(hi)); return r; }
;     __device__ __forceinline__ void operator()(const f32x4 (&acc)[2][2][4][2], const Unit& u, int wr, int wc, int fr, int fq) const {
;     ...
;                 for (int m = 0; m < 4; ++m) {
;                     const f32x4 g = acc[ai][1][m][n] * rs[ai][m], v = acc[ai][0][m][n] * rs[ai][m];
;                     f32x4 r1, r2, a;
; #pragma unroll
;                     for (int e = 0; e < 4; ++e) { r1[e] = __shfl(g[e], src1); r2[e] = __shfl(g[e], src2); }
; #pragma unroll
;                     for (int e = 0; e < 4; ++e) {
;                         const float p1 = fr >= 1 ? r1[e] : r1p[e], p2 = fr >= 2 ? r2[e] : r2p[e];
;                         const float gg = b4[e] + w0[e] * p2 + w1[e] * p1 + w2[e] * g[e];
;                         a[e] = gg * __builtin_amdgcn_rcpf(1.f + __expf(-gg)) * v[e];
;                     }
;                     r1p = r1; r2p = r2;
;                     const size_t row = (size_t)(u.pm * BM + ai * HALF + wr * 64 + m * 16 + fr);
;                     if (m == 0 && fr < 2) {
;                         *(f32x4*)(GF + (size_t)(slab * 2 + fr) * FF + cbase) = g; *(f32x4*)(VF + (size_t)(slab * 2 + fr) * FF + cbase) = v;
;                     } else {
;                         typedef unsigned u32x2v __attribute__((ext_vector_type(2)));
;                         u32x2v w; w.x = cvt_pk_bf16(a[0], a[1]); w.y = cvt_pk_bf16(a[2], a[3]);
;                         *(u32x2v*)(ACT + row * FF + cbase) = w;
;                     }
;                     if (m == 3 && fr >= 14) *(f32x4*)(GL + (size_t)(slab * 2 + fr - 14) * FF + cbase) = g;
	v_cndmask_b32_e64 v65, v44, v55, s[40:41]
	v_mov_b32_e32 v44, v41
	s_waitcnt lgkmcnt(1)
	v_cndmask_b32_e64 v50, v59, v50, s[42:43]
	v_pk_mul_f32 v[44:45], v[44:45], v[64:65]
	v_fma_f32 v50, v69, v50, v73
	v_add_f32_e32 v45, v45, v50
	v_add_f32_e32 v44, v44, v45
	v_mul_f32_e32 v45, 0xbfb8aa3b, v44
	v_exp_f32_e32 v45, v45
	ds_bpermute_b32 v50, v161, v40
	v_mov_b32_e32 v43, v80
	v_mov_b32_e32 v135, v134
	v_add_f32_e32 v42, 1.0, v45
	v_rcp_f32_e32 v45, v42
	s_waitcnt lgkmcnt(0)
	v_cndmask_b32_e64 v77, v50, v53, s[40:41]
	v_mov_b32_e32 v42, v40
	v_cndmask_b32_e64 v50, v60, v51, s[42:43]
	v_pk_mul_f32 v[42:43], v[42:43], v[76:77]
	v_fma_f32 v50, v68, v50, v72
	v_add_f32_e32 v43, v43, v50
	v_add_f32_e32 v50, v42, v43
	v_pk_mul_f32 v[38:39], v[38:39], v[134:135]
	v_mul_f32_e32 v42, 0xbfb8aa3b, v50
	ds_bpermute_b32 v48, v161, v39
	ds_bpermute_b32 v49, v200, v39
	v_exp_f32_e32 v42, v42
	v_mul_f32_e32 v43, v44, v45
	ds_bpermute_b32 v46, v161, v38
	ds_bpermute_b32 v47, v200, v38
	v_add_f32_e32 v42, 1.0, v42
	v_mul_f32_e32 v37, v37, v43
	v_rcp_f32_e32 v44, v42
	s_waitcnt lgkmcnt(3)
	v_cndmask_b32_e64 v63, v48, v57, s[40:41]
	v_mov_b32_e32 v42, v39
	v_mov_b32_e32 v43, v79
	s_waitcnt lgkmcnt(2)
	v_cndmask_b32_e64 v45, v58, v49, s[42:43]
	v_pk_mul_f32 v[42:43], v[42:43], v[62:63]
	v_fma_f32 v45, v67, v45, v71
	v_add_f32_e32 v43, v43, v45
	v_add_f32_e32 v45, v42, v43
	v_mul_f32_e32 v42, 0xbfb8aa3b, v45
	v_exp_f32_e32 v48, v42
	s_waitcnt lgkmcnt(1)
	v_cndmask_b32_e64 v75, v46, v54, s[40:41]
	v_mov_b32_e32 v42, v38
	v_mov_b32_e32 v43, v78
	s_waitcnt lgkmcnt(0)
	v_cndmask_b32_e64 v46, v56, v47, s[42:43]
	v_pk_mul_f32 v[42:43], v[42:43], v[74:75]
	v_fma_f32 v46, v66, v46, v70
	v_add_f32_e32 v43, v43, v46
	v_add_f32_e32 v42, v42, v43
	v_mul_f32_e32 v43, 0xbfb8aa3b, v42
	v_exp_f32_e32 v43, v43
	v_add_f32_e32 v46, 1.0, v48
	v_rcp_f32_e32 v46, v46
	v_mul_f32_e32 v44, v50, v44
	v_add_f32_e32 v43, 1.0, v43
	v_rcp_f32_e32 v43, v43
	v_pk_mul_f32 v[34:35], v[34:35], v[134:135]
	v_mul_f32_e32 v36, v36, v44
	v_mul_f32_e32 v44, v45, v46
	v_mul_f32_e32 v42, v42, v43
	v_mul_f32_e32 v35, v35, v44
	v_mul_f32_e32 v34, v34, v42
	v_cvt_pk_bf16_f32 v34, v34, v35
	v_cvt_pk_bf16_f32 v35, v36, v37
	s_nop 1
	v_permlane16_swap_b32_e32 v210, v34
	v_permlane16_swap_b32_e32 v211, v35
	v_mov_b32_e32 v220, v210
	v_mov_b32_e32 v221, v211
	v_mov_b32_e32 v222, v34
	v_mov_b32_e32 v223, v35
	v_add_co_u32_e64 v110, s[98:99], v110, v205
	s_nop 1
	v_addc_co_u32_e64 v111, s[98:99], 0, v111, s[98:99]
	global_store_dwordx4 v[110:111], v[220:223], off
	s_and_saveexec_b64 s[10:11], s[44:45]
	s_cbranch_execz .LBB0_59
	global_store_dwordx4 v[106:107], v[38:41], off offset:64
.LBB0_59:
	s_or_b64 exec, exec, s[10:11]
	v_mov_b32_e32 v103, v102
	v_mov_b32_e32 v42, v102
	v_mov_b32_e32 v43, v102
	v_pk_mul_f32 v[36:37], v[28:29], v[42:43]
	v_pk_mul_f32 v[34:35], v[26:27], v[102:103]
	ds_bpermute_b32 v75, v161, v34
	ds_bpermute_b32 v38, v200, v34
	ds_bpermute_b32 v63, v161, v35
	ds_bpermute_b32 v39, v200, v35
	ds_bpermute_b32 v77, v161, v36
	ds_bpermute_b32 v40, v200, v36
	ds_bpermute_b32 v65, v161, v37
	ds_bpermute_b32 v41, v200, v37
	v_pk_mul_f32 v[28:29], v[32:33], v[42:43]
	v_pk_mul_f32 v[26:27], v[30:31], v[102:103]
	s_and_saveexec_b64 s[10:11], s[42:43]
	s_xor_b64 s[10:11], exec, s[10:11]
	s_cbranch_execz .LBB0_61
	v_mov_b32_e32 v30, v37
	v_mov_b32_e32 v31, v81
	s_waitcnt lgkmcnt(1)
	v_pk_mul_f32 v[30:31], v[30:31], v[64:65]
	s_waitcnt lgkmcnt(0)
	v_fma_f32 v32, v69, v41, v73
	v_add_f32_e32 v31, v31, v32
	v_add_f32_e32 v30, v30, v31
	v_mul_f32_e32 v31, 0xbfb8aa3b, v30
	v_exp_f32_e32 v31, v31
	v_mov_b32_e32 v37, v80
	v_add_f32_e32 v31, 1.0, v31
	v_rcp_f32_e32 v31, v31
	s_nop 0
	v_mul_f32_e32 v30, v30, v31
	v_mul_f32_e32 v32, v29, v30
	v_pk_mul_f32 v[30:31], v[36:37], v[76:77]
	v_fma_f32 v29, v68, v40, v72
	v_add_f32_e32 v29, v31, v29
	v_add_f32_e32 v29, v30, v29
	v_mul_f32_e32 v30, 0xbfb8aa3b, v29
	v_exp_f32_e32 v30, v30
	v_fma_f32 v31, v67, v39, v71
	v_add_f32_e32 v30, 1.0, v30
	v_rcp_f32_e32 v30, v30
	s_nop 0
	v_mul_f32_e32 v29, v29, v30
	v_mul_f32_e32 v30, v28, v29
	v_mov_b32_e32 v28, v35
	v_mov_b32_e32 v29, v79
	v_pk_mul_f32 v[28:29], v[28:29], v[62:63]
	v_mov_b32_e32 v35, v78
	v_add_f32_e32 v29, v29, v31
	v_add_f32_e32 v28, v28, v29
	v_mul_f32_e32 v29, 0xbfb8aa3b, v28
	v_exp_f32_e32 v29, v29
	v_fma_f32 v31, v66, v38, v70
	v_add_f32_e32 v29, 1.0, v29
	v_rcp_f32_e32 v29, v29
	s_nop 0
	v_mul_f32_e32 v28, v28, v29
	v_mul_f32_e32 v27, v27, v28
	v_pk_mul_f32 v[28:29], v[34:35], v[74:75]
	s_nop 0
	v_add_f32_e32 v29, v29, v31
	v_add_f32_e32 v28, v28, v29
	v_mul_f32_e32 v29, 0xbfb8aa3b, v28
	v_exp_f32_e32 v29, v29
	s_nop 0
	v_add_f32_e32 v29, 1.0, v29
	v_rcp_f32_e32 v29, v29
	s_nop 0
	v_mul_f32_e32 v28, v28, v29
	v_mul_f32_e32 v26, v26, v28
	v_mov_b64_e32 v[28:29], s[48:49]
	v_mad_i64_i32 v[28:29], s[12:13], v180, s17, v[28:29]
	v_cvt_pk_bf16_f32 v26, v26, v27
	v_cvt_pk_bf16_f32 v27, v30, v32
	v_lshl_add_u64 v[28:29], v[156:157], 1, v[28:29]
	s_nop 1
	v_permlane16_swap_b32_e32 v212, v26
	v_permlane16_swap_b32_e32 v213, v27
	v_mov_b32_e32 v220, v212
	v_mov_b32_e32 v221, v213
	v_mov_b32_e32 v222, v26
	v_mov_b32_e32 v223, v27
	v_add_co_u32_e64 v28, s[98:99], v28, v205
	s_nop 1
	v_addc_co_u32_e64 v29, s[98:99], 0, v29, s[98:99]
	global_store_dwordx4 v[28:29], v[220:223], off

; __device__ __forceinline__ unsigned cvt_pk_bf16(float lo, float hi) { unsigned r; asm volatile("v_cvt_pk_bf16_f32 %0, %1, %2" : "=v"(r) : "v"(lo), "v"(hi)); return r; }
;     __device__ __forceinline__ void operator()(const f32x4 (&acc)[2][2][4][2], const Unit& u, int wr, int wc, int fr, int fq) const {
;     ...
;                 for (int m = 0; m < 4; ++m) {
;                     const f32x4 g = acc[ai][1][m][n] * rs[ai][m], v = acc[ai][0][m][n] * rs[ai][m];
;                     f32x4 r1, r2, a;
; #pragma unroll
;                     for (int e = 0; e < 4; ++e) { r1[e] = __shfl(g[e], src1); r2[e] = __shfl(g[e], src2); }
; #pragma unroll
;                     for (int e = 0; e < 4; ++e) {
;                         const float p1 = fr >= 1 ? r1[e] : r1p[e], p2 = fr >= 2 ? r2[e] : r2p[e];
;                         const float gg = b4[e] + w0[e] * p2 + w1[e] * p1 + w2[e] * g[e];
;                         a[e] = gg * __builtin_amdgcn_rcpf(1.f + __expf(-gg)) * v[e];
;                     }
;                     r1p = r1; r2p = r2;
;                     const size_t row = (size_t)(u.pm * BM + ai * HALF + wr * 64 + m * 16 + fr);
;                     if (m == 0 && fr < 2) {
;                         *(f32x4*)(GF + (size_t)(slab * 2 + fr) * FF + cbase) = g; *(f32x4*)(VF + (size_t)(slab * 2 + fr) * FF + cbase) = v;
;                     } else {
;                         typedef unsigned u32x2v __attribute__((ext_vector_type(2)));
;                         u32x2v w; w.x = cvt_pk_bf16(a[0], a[1]); w.y = cvt_pk_bf16(a[2], a[3]);
;                         *(u32x2v*)(ACT + row * FF + cbase) = w;
;                     }
;                     if (m == 3 && fr >= 14) *(f32x4*)(GL + (size_t)(slab * 2 + fr - 14) * FF + cbase) = g;
.LBB0_63:
	s_or_b64 exec, exec, s[10:11]
	s_nop 0
	v_mov_b32_e32 v26, v94
	v_mov_b32_e32 v27, v94
	v_pk_mul_f32 v[24:25], v[24:25], v[26:27]
	ds_bpermute_b32 v31, v161, v25
	ds_bpermute_b32 v35, v200, v25
	v_mov_b32_e32 v28, v25
	v_mov_b32_e32 v29, v81
	ds_bpermute_b32 v36, v200, v24
	s_waitcnt lgkmcnt(2)
	v_cndmask_b32_e64 v65, v31, v65, s[40:41]
	s_waitcnt lgkmcnt(1)
	v_cndmask_b32_e64 v25, v41, v35, s[42:43]
	v_pk_mul_f32 v[28:29], v[28:29], v[64:65]
	v_fma_f32 v25, v69, v25, v73
	v_add_f32_e32 v25, v29, v25
	v_add_f32_e32 v28, v28, v25
	v_mul_f32_e32 v25, 0xbfb8aa3b, v28
	v_exp_f32_e32 v25, v25
	ds_bpermute_b32 v29, v161, v24
	v_pk_mul_f32 v[20:21], v[20:21], v[26:27]
	s_waitcnt lgkmcnt(1)
	v_cndmask_b32_e64 v27, v40, v36, s[42:43]
	v_add_f32_e32 v25, 1.0, v25
	v_rcp_f32_e32 v26, v25
	s_waitcnt lgkmcnt(0)
	v_cndmask_b32_e64 v77, v29, v77, s[40:41]
	v_mov_b32_e32 v25, v80
	v_pk_mul_f32 v[24:25], v[24:25], v[76:77]
	v_fma_f32 v27, v68, v27, v72
	v_add_f32_e32 v25, v25, v27
	v_mov_b32_e32 v95, v94
	v_add_f32_e32 v27, v24, v25
	v_pk_mul_f32 v[22:23], v[22:23], v[94:95]
	v_mul_f32_e32 v24, 0xbfb8aa3b, v27
	ds_bpermute_b32 v33, v161, v23
	ds_bpermute_b32 v34, v200, v23
	v_exp_f32_e32 v24, v24
	v_mul_f32_e32 v25, v28, v26
	ds_bpermute_b32 v30, v161, v22
	ds_bpermute_b32 v32, v200, v22
	v_add_f32_e32 v24, 1.0, v24
	v_mul_f32_e32 v21, v21, v25
	v_rcp_f32_e32 v26, v24
	s_waitcnt lgkmcnt(3)
	v_cndmask_b32_e64 v63, v33, v63, s[40:41]
	v_mov_b32_e32 v24, v23
	v_mov_b32_e32 v25, v79
	s_waitcnt lgkmcnt(2)
	v_cndmask_b32_e64 v23, v39, v34, s[42:43]
	v_pk_mul_f32 v[24:25], v[24:25], v[62:63]
	v_fma_f32 v23, v67, v23, v71
	v_add_f32_e32 v23, v25, v23
	v_add_f32_e32 v24, v24, v23
	v_mul_f32_e32 v23, 0xbfb8aa3b, v24
	v_exp_f32_e32 v25, v23
	s_waitcnt lgkmcnt(1)
	v_cndmask_b32_e64 v75, v30, v75, s[40:41]
	v_mov_b32_e32 v23, v78
	s_waitcnt lgkmcnt(0)
	v_cndmask_b32_e64 v28, v38, v32, s[42:43]
	v_pk_mul_f32 v[22:23], v[22:23], v[74:75]
	v_fma_f32 v28, v66, v28, v70
	v_add_f32_e32 v23, v23, v28
	v_add_f32_e32 v22, v22, v23
	v_mul_f32_e32 v23, 0xbfb8aa3b, v22
	v_exp_f32_e32 v23, v23
	v_add_f32_e32 v25, 1.0, v25
	v_rcp_f32_e32 v25, v25
	v_pk_mul_f32 v[18:19], v[18:19], v[94:95]
	v_add_f32_e32 v23, 1.0, v23
	v_rcp_f32_e32 v23, v23
	v_mul_f32_e32 v24, v24, v25
	v_mul_f32_e32 v26, v27, v26
	v_mul_f32_e32 v19, v19, v24
	v_mul_f32_e32 v22, v22, v23
	v_mul_f32_e32 v18, v18, v22
	v_mul_f32_e32 v20, v20, v26
	v_cvt_pk_bf16_f32 v18, v18, v19
	v_cvt_pk_bf16_f32 v19, v20, v21
	s_nop 1
	v_permlane16_swap_b32_e32 v214, v18
	v_permlane16_swap_b32_e32 v215, v19
	v_mov_b32_e32 v220, v214
	v_mov_b32_e32 v221, v215
	v_mov_b32_e32 v222, v18
	v_mov_b32_e32 v223, v19
	v_add_co_u32_e64 v98, s[98:99], v98, v205
	s_nop 1
	v_addc_co_u32_e64 v99, s[98:99], 0, v99, s[98:99]
	global_store_dwordx4 v[98:99], v[220:223], off
	v_mov_b32_e32 v18, v92
	v_mov_b32_e32 v19, v92
	v_pk_mul_f32 v[16:17], v[16:17], v[18:19]
	ds_bpermute_b32 v23, v161, v17
	ds_bpermute_b32 v27, v200, v17
	v_mov_b32_e32 v20, v17
	v_mov_b32_e32 v21, v81
	ds_bpermute_b32 v28, v200, v16
	s_waitcnt lgkmcnt(2)
	v_cndmask_b32_e64 v65, v23, v31, s[40:41]
	s_waitcnt lgkmcnt(1)
	v_cndmask_b32_e64 v17, v35, v27, s[42:43]
	v_pk_mul_f32 v[20:21], v[20:21], v[64:65]
	v_fma_f32 v17, v69, v17, v73
	v_add_f32_e32 v17, v21, v17
	v_add_f32_e32 v20, v20, v17
	v_mul_f32_e32 v17, 0xbfb8aa3b, v20
	v_exp_f32_e32 v17, v17
	ds_bpermute_b32 v21, v161, v16
	v_pk_mul_f32 v[12:13], v[12:13], v[18:19]
	s_waitcnt lgkmcnt(1)
	v_cndmask_b32_e64 v19, v36, v28, s[42:43]
	v_add_f32_e32 v17, 1.0, v17
	v_rcp_f32_e32 v18, v17
	s_waitcnt lgkmcnt(0)
	v_cndmask_b32_e64 v77, v21, v29, s[40:41]
	v_mov_b32_e32 v17, v80
	v_pk_mul_f32 v[16:17], v[16:17], v[76:77]
	v_fma_f32 v19, v68, v19, v72
	v_add_f32_e32 v17, v17, v19
	v_mov_b32_e32 v93, v92
	v_add_f32_e32 v19, v16, v17
	v_pk_mul_f32 v[14:15], v[14:15], v[92:93]
	v_mul_f32_e32 v16, 0xbfb8aa3b, v19
	ds_bpermute_b32 v25, v161, v15
	ds_bpermute_b32 v26, v200, v15
	v_exp_f32_e32 v16, v16
	v_mul_f32_e32 v17, v20, v18
	ds_bpermute_b32 v22, v161, v14
	ds_bpermute_b32 v24, v200, v14
	v_add_f32_e32 v16, 1.0, v16
	v_mul_f32_e32 v13, v13, v17
	v_rcp_f32_e32 v18, v16
	s_waitcnt lgkmcnt(3)
; __device__ __forceinline__ unsigned cvt_pk_bf16(float lo, float hi) { unsigned r; asm volatile("v_cvt_pk_bf16_f32 %0, %1, %2" : "=v"(r) : "v"(lo), "v"(hi)); return r; }
;     __device__ __forceinline__ void operator()(const f32x4 (&acc)[2][2][4][2], const Unit& u, int wr, int wc, int fr, int fq) const {
;     ...
;                 for (int m = 0; m < 4; ++m) {
;                     const f32x4 g = acc[ai][1][m][n] * rs[ai][m], v = acc[ai][0][m][n] * rs[ai][m];
;                     f32x4 r1, r2, a;
; #pragma unroll
;                     for (int e = 0; e < 4; ++e) { r1[e] = __shfl(g[e], src1); r2[e] = __shfl(g[e], src2); }
; #pragma unroll
;                     for (int e = 0; e < 4; ++e) {
;                         const float p1 = fr >= 1 ? r1[e] : r1p[e], p2 = fr >= 2 ? r2[e] : r2p[e];
;                         const float gg = b4[e] + w0[e] * p2 + w1[e] * p1 + w2[e] * g[e];
;                         a[e] = gg * __builtin_amdgcn_rcpf(1.f + __expf(-gg)) * v[e];
;                     }
;                     r1p = r1; r2p = r2;
;                     const size_t row = (size_t)(u.pm * BM + ai * HALF + wr * 64 + m * 16 + fr);
;                     if (m == 0 && fr < 2) {
;                         *(f32x4*)(GF + (size_t)(slab * 2 + fr) * FF + cbase) = g; *(f32x4*)(VF + (size_t)(slab * 2 + fr) * FF + cbase) = v;
;                     } else {
;                         typedef unsigned u32x2v __attribute__((ext_vector_type(2)));
;                         u32x2v w; w.x = cvt_pk_bf16(a[0], a[1]); w.y = cvt_pk_bf16(a[2], a[3]);
;                         *(u32x2v*)(ACT + row * FF + cbase) = w;
;                     }
;                     if (m == 3 && fr >= 14) *(f32x4*)(GL + (size_t)(slab * 2 + fr - 14) * FF + cbase) = g;
	v_cndmask_b32_e64 v63, v25, v33, s[40:41]
	v_mov_b32_e32 v16, v15
	v_mov_b32_e32 v17, v79
	s_waitcnt lgkmcnt(2)
	v_cndmask_b32_e64 v15, v34, v26, s[42:43]
	v_pk_mul_f32 v[16:17], v[16:17], v[62:63]
	v_fma_f32 v15, v67, v15, v71
	v_add_f32_e32 v15, v17, v15
	v_add_f32_e32 v16, v16, v15
	v_mul_f32_e32 v15, 0xbfb8aa3b, v16
	v_exp_f32_e32 v17, v15
	s_waitcnt lgkmcnt(1)
	v_cndmask_b32_e64 v75, v22, v30, s[40:41]
	v_mov_b32_e32 v15, v78
	s_waitcnt lgkmcnt(0)
	v_cndmask_b32_e64 v20, v32, v24, s[42:43]
	v_pk_mul_f32 v[14:15], v[14:15], v[74:75]
	v_fma_f32 v20, v66, v20, v70
	v_add_f32_e32 v15, v15, v20
	v_add_f32_e32 v14, v14, v15
	v_mul_f32_e32 v15, 0xbfb8aa3b, v14
	v_exp_f32_e32 v15, v15
	v_add_f32_e32 v17, 1.0, v17
	v_rcp_f32_e32 v17, v17
	v_pk_mul_f32 v[10:11], v[10:11], v[92:93]
	v_add_f32_e32 v15, 1.0, v15
	v_rcp_f32_e32 v15, v15
	v_mul_f32_e32 v16, v16, v17
	v_mul_f32_e32 v18, v19, v18
	v_mul_f32_e32 v11, v11, v16
	v_mul_f32_e32 v14, v14, v15
	v_mul_f32_e32 v10, v10, v14
	v_mul_f32_e32 v12, v12, v18
	v_cvt_pk_bf16_f32 v10, v10, v11
	v_cvt_pk_bf16_f32 v11, v12, v13
	s_nop 1
	v_permlane16_swap_b32_e32 v216, v10
	v_permlane16_swap_b32_e32 v217, v11
	v_mov_b32_e32 v220, v216
	v_mov_b32_e32 v221, v217
	v_mov_b32_e32 v222, v10
	v_mov_b32_e32 v223, v11
	v_add_co_u32_e64 v96, s[98:99], v96, v205
	s_nop 1
	v_addc_co_u32_e64 v97, s[98:99], 0, v97, s[98:99]
	global_store_dwordx4 v[96:97], v[220:223], off
	v_mov_b32_e32 v10, v90
	v_mov_b32_e32 v11, v90
	v_pk_mul_f32 v[8:9], v[8:9], v[10:11]
	ds_bpermute_b32 v12, v161, v9
	ds_bpermute_b32 v18, v200, v9
	v_mov_b32_e32 v13, v81
	ds_bpermute_b32 v19, v200, v8
	v_pk_mul_f32 v[4:5], v[4:5], v[10:11]
	s_waitcnt lgkmcnt(2)
	v_cndmask_b32_e64 v65, v12, v23, s[40:41]
	v_mov_b32_e32 v12, v9
	s_waitcnt lgkmcnt(1)
	v_cndmask_b32_e64 v18, v27, v18, s[42:43]
	v_pk_mul_f32 v[12:13], v[12:13], v[64:65]
	v_fma_f32 v18, v69, v18, v73
	v_add_f32_e32 v13, v13, v18
	v_add_f32_e32 v12, v12, v13
	v_mul_f32_e32 v13, 0xbfb8aa3b, v12
	v_exp_f32_e32 v13, v13
	ds_bpermute_b32 v18, v161, v8
	v_mov_b32_e32 v11, v80
	v_mov_b32_e32 v91, v90
	v_add_f32_e32 v10, 1.0, v13
	v_rcp_f32_e32 v13, v10
	s_waitcnt lgkmcnt(0)
	v_cndmask_b32_e64 v77, v18, v21, s[40:41]
	v_mov_b32_e32 v10, v8
	v_cndmask_b32_e64 v18, v28, v19, s[42:43]
	v_pk_mul_f32 v[10:11], v[10:11], v[76:77]
	v_fma_f32 v18, v68, v18, v72
	v_add_f32_e32 v11, v11, v18
	v_add_f32_e32 v18, v10, v11
	v_pk_mul_f32 v[6:7], v[6:7], v[90:91]
	v_mul_f32_e32 v10, 0xbfb8aa3b, v18
	ds_bpermute_b32 v16, v161, v7
	ds_bpermute_b32 v17, v200, v7
	v_exp_f32_e32 v10, v10
	v_mul_f32_e32 v11, v12, v13
	ds_bpermute_b32 v14, v161, v6
	ds_bpermute_b32 v15, v200, v6
	v_add_f32_e32 v10, 1.0, v10
	v_mul_f32_e32 v5, v5, v11
	v_rcp_f32_e32 v12, v10
	s_waitcnt lgkmcnt(3)
	v_cndmask_b32_e64 v63, v16, v25, s[40:41]
	v_mov_b32_e32 v10, v7
	v_mov_b32_e32 v11, v79
	s_waitcnt lgkmcnt(2)
	v_cndmask_b32_e64 v13, v26, v17, s[42:43]
	v_pk_mul_f32 v[10:11], v[10:11], v[62:63]
	v_fma_f32 v13, v67, v13, v71
	v_add_f32_e32 v11, v11, v13
	v_add_f32_e32 v13, v10, v11
	v_mul_f32_e32 v10, 0xbfb8aa3b, v13
	v_exp_f32_e32 v16, v10
	s_waitcnt lgkmcnt(1)
	v_cndmask_b32_e64 v75, v14, v22, s[40:41]
	v_mov_b32_e32 v10, v6
	v_mov_b32_e32 v11, v78
	s_waitcnt lgkmcnt(0)
	v_cndmask_b32_e64 v14, v24, v15, s[42:43]
	v_pk_mul_f32 v[10:11], v[10:11], v[74:75]
	v_fmac_f32_e32 v70, v66, v14
	v_add_f32_e32 v11, v11, v70
	v_add_f32_e32 v10, v10, v11
	v_mul_f32_e32 v11, 0xbfb8aa3b, v10
	v_exp_f32_e32 v11, v11
	v_add_f32_e32 v14, 1.0, v16
	v_rcp_f32_e32 v14, v14
	v_mul_f32_e32 v12, v18, v12
	v_add_f32_e32 v11, 1.0, v11
	v_rcp_f32_e32 v11, v11
	v_pk_mul_f32 v[2:3], v[2:3], v[90:91]
	v_mul_f32_e32 v4, v4, v12
	v_mul_f32_e32 v12, v13, v14
	v_mul_f32_e32 v10, v10, v11
	v_mul_f32_e32 v3, v3, v12
	v_mul_f32_e32 v2, v2, v10
	v_cvt_pk_bf16_f32 v2, v2, v3
	v_cvt_pk_bf16_f32 v3, v4, v5
	s_nop 1
	v_permlane16_swap_b32_e32 v218, v2
	v_permlane16_swap_b32_e32 v219, v3
	v_mov_b32_e32 v220, v218
	v_mov_b32_e32 v221, v219
	v_mov_b32_e32 v222, v2
	v_mov_b32_e32 v223, v3
	v_add_co_u32_e64 v88, s[98:99], v88, v205
	s_nop 1
	v_addc_co_u32_e64 v89, s[98:99], 0, v89, s[98:99]
	global_store_dwordx4 v[88:89], v[220:223], off
	s_and_saveexec_b64 s[10:11], s[44:45]
	s_cbranch_execz .LBB0_65
	global_store_dwordx4 v[86:87], v[6:9], off offset:64

; #define MFMA32(a, b, c) __builtin_amdgcn_mfma_f32_32x32x16_bf16((a), (b), (c), 0, 0, 0)
; DI bf16x8 pack8(const f32x16& x, int s) { u32x4 p; p[0] = cvtpk(x[8 * s], x[8 * s + 1]); p[1] = cvtpk(x[8 * s + 2], x[8 * s + 3]); p[2] = cvtpk(x[8 * s + 4], x[8 * s + 5]); p[3] = cvtpk(x[8 * s + 6], x[8 * s + 7]); return __builtin_bit_cast(bf16x8, p); }
; #define AT_LWRITE(buf) do { LAS char* kb_ = lds + (buf) * BUFB + srow * PITCH + sch * 16; \
;         _Pragma("unroll") for (int i_ = 0; i_ < PER; ++i_) { *(LAS u32x4*)(kb_ + 16 * i_) = kreg[i_]; *(LAS u32x4*)(kb_ + TILEB + 16 * i_) = vreg[i_]; } \
;         if (MODE == 1 && tid < 64) *(LAS float*)(lds + (buf) * BUFB + 2 * TILEB + 4 * tid) = ckreg; } while (0)
; template <int DH, int MODE>
; DI void attn_unit(LAS char* lds, const AttnU& u, const LAS float* tbl) {
;     ...
;                 const float mref = (m == -INFINITY) ? 0.f : m;
; #pragma unroll
;                 for (int r = 0; r < 16; ++r) { p[r] = __builtin_amdgcn_exp2f(p[r] - mref); l += p[r]; }
;                 const bf16x8 pb0 = pack8(p, 0), pb1 = pack8(p, 1);
; #pragma unroll
;                 for (int db = 0; db < DH / 32; ++db) {
;                     const bf16x8 v0 = frag_tr_perm(Vt, PITCH, 32 * sub, 32 * db, lane), v1 = frag_tr_perm(Vt, PITCH, 32 * sub + 16, 32 * db, lane);
;                     o[db] = MFMA32(v0, pb0, o[db]); o[db] = MFMA32(v1, pb1, o[db]);
;                 }
;             }
;         }
;         if (t + 1 < NT) AT_LWRITE(cur ^ 1);
;         __syncthreads();
;     }
;     ...
;     l += __shfl_xor(l, 32);
.LBB0_133:
	v_sub_f32_e32 v4, v80, v3
	v_exp_f32_e32 v96, v4
	v_sub_f32_e32 v4, v81, v3
	v_exp_f32_e32 v97, v4
	v_sub_f32_e32 v4, v82, v3
	v_exp_f32_e32 v98, v4
	v_sub_f32_e32 v4, v83, v3
	v_exp_f32_e32 v99, v4
	v_sub_f32_e32 v4, v84, v3
	v_exp_f32_e32 v84, v4
	v_sub_f32_e32 v4, v85, v3
	v_exp_f32_e32 v85, v4
	v_sub_f32_e32 v4, v86, v3
	v_exp_f32_e32 v86, v4
	v_sub_f32_e32 v4, v87, v3
	v_exp_f32_e32 v87, v4
	v_sub_f32_e32 v4, v88, v3
	v_exp_f32_e32 v88, v4
	v_sub_f32_e32 v4, v89, v3
	v_exp_f32_e32 v89, v4
	v_sub_f32_e32 v4, v90, v3
	v_exp_f32_e32 v90, v4
	v_sub_f32_e32 v4, v91, v3
	ds_read_b64_tr_b16 v[12:13], v0 offset:61184
	ds_read_b64_tr_b16 v[14:15], v0 offset:63360
	v_exp_f32_e32 v91, v4
	v_sub_f32_e32 v4, v92, v3
	v_exp_f32_e32 v92, v4
	v_sub_f32_e32 v4, v93, v3
	v_exp_f32_e32 v93, v4
	v_sub_f32_e32 v4, v94, v3
	v_exp_f32_e32 v94, v4
	v_cvt_pk_bf16_f32 v4, v96, v97
	v_cvt_pk_bf16_f32 v5, v98, v99
	v_cvt_pk_bf16_f32 v6, v84, v85
	v_cvt_pk_bf16_f32 v7, v86, v87
	v_sub_f32_e32 v3, v95, v3
	v_add_u32_e32 v95, 0xcd00, v0
	s_waitcnt lgkmcnt(0)
	v_mfma_f32_32x32x16_bf16 v[64:79], v[12:15], v[4:7], v[64:79]
	v_exp_f32_e32 v3, v3
	ds_read_b64_tr_b16 v[80:81], v95 offset:13056
	ds_read_b64_tr_b16 v[82:83], v95 offset:15232
	v_cvt_pk_bf16_f32 v8, v88, v89
	v_cvt_pk_bf16_f32 v9, v90, v91
	v_cvt_pk_bf16_f32 v10, v92, v93
	v_cvt_pk_bf16_f32 v11, v94, v3
	s_add_u32 s6, s94, s14
	s_addc_u32 s7, s95, s15
	s_waitcnt lgkmcnt(0)
	v_mfma_f32_32x32x16_bf16 v[64:79], v[80:83], v[8:11], v[64:79]
	ds_read_b64_tr_b16 v[12:13], v0 offset:61248
	ds_read_b64_tr_b16 v[14:15], v0 offset:63424
	ds_read_b64_tr_b16 v[80:81], v95 offset:13120
	ds_read_b64_tr_b16 v[82:83], v95 offset:15296
	s_lshl_b32 s5, s5, 1
	s_add_u32 s6, s6, s5
	s_addc_u32 s7, s7, 0
	s_add_i32 s4, s4, s92
	s_add_i32 s1, s1, s2
	s_cmpk_gt_i32 s4, 0x1ff
	s_waitcnt lgkmcnt(2)
	v_mfma_f32_32x32x16_bf16 v[48:63], v[12:15], v[4:7], v[48:63]
	s_waitcnt lgkmcnt(0)
	v_mfma_f32_32x32x16_bf16 v[48:63], v[80:83], v[8:11], v[48:63]
	ds_read_b64_tr_b16 v[12:13], v0 offset:61312
	ds_read_b64_tr_b16 v[14:15], v0 offset:63488
	ds_read_b64_tr_b16 v[80:81], v95 offset:13184
	ds_read_b64_tr_b16 v[82:83], v95 offset:15360
	s_waitcnt lgkmcnt(2)
	v_mfma_f32_32x32x16_bf16 v[32:47], v[12:15], v[4:7], v[32:47]
	s_waitcnt lgkmcnt(0)
	v_mfma_f32_32x32x16_bf16 v[32:47], v[80:83], v[8:11], v[32:47]
	ds_read_b64_tr_b16 v[12:13], v0 offset:61376
	ds_read_b64_tr_b16 v[14:15], v0 offset:63552
	ds_read_b64_tr_b16 v[80:81], v95 offset:13248
	ds_read_b64_tr_b16 v[82:83], v95 offset:15424
	v_add_f32_e32 v0, v96, v2
	v_add_f32_e32 v0, v97, v0
	v_add_f32_e32 v0, v98, v0
	v_add_f32_e32 v0, v99, v0
	v_add_f32_e32 v0, v84, v0
	v_add_f32_e32 v0, v85, v0
	v_add_f32_e32 v0, v86, v0
	v_add_f32_e32 v0, v87, v0
	v_add_f32_e32 v0, v88, v0
	v_add_f32_e32 v0, v89, v0
	v_add_f32_e32 v0, v90, v0
	v_add_f32_e32 v0, v91, v0
	v_add_f32_e32 v0, v92, v0
	v_add_f32_e32 v0, v93, v0
	v_add_f32_e32 v0, v94, v0
	v_add_f32_e32 v0, v3, v0
	ds_bpermute_b32 v2, v137, v0
	s_waitcnt lgkmcnt(3)
	v_mfma_f32_32x32x16_bf16 v[16:31], v[12:15], v[4:7], v[16:31]
	s_waitcnt lgkmcnt(0)
	s_barrier
; DI unsigned cvtpk(float lo, float hi) { f32x2_t v = {lo, hi}; bf16x2_t b = __builtin_convertvector(v, bf16x2_t); return __builtin_bit_cast(unsigned, b); }
; template <int DH, int MODE>
; DI void attn_unit(LAS char* lds, const AttnU& u, const LAS float* tbl) {
;     ...
;     l += __shfl_xor(l, 32);
;     const float inv = 1.f / l;
;     bf16* orow = u.Ob + (long)(32 * w + r32) * u.ostride;
; #pragma unroll
;     for (int db = 0; db < DH / 32; ++db)
; #pragma unroll
;         for (int g = 0; g < 4; ++g) { u32x2 wv; wv.x = cvtpk(o[db][4 * g] * inv, o[db][4 * g + 1] * inv); wv.y = cvtpk(o[db][4 * g + 2] * inv, o[db][4 * g + 3] * inv);
;             *(u32x2*)(orow + 32 * db + 8 * g + 4 * hi) = wv; }
	v_add_f32_e32 v0, v0, v2
	v_div_scale_f32 v2, s[10:11], v0, v0, 1.0
	v_rcp_f32_e32 v3, v2
	v_mfma_f32_32x32x16_bf16 v[16:31], v[80:83], v[8:11], v[16:31]
	v_fma_f32 v4, -v2, v3, 1.0
	v_fmac_f32_e32 v3, v4, v3
	v_div_scale_f32 v4, vcc, 1.0, v0, 1.0
	v_mul_f32_e32 v5, v4, v3
	v_fma_f32 v6, -v2, v5, v4
	v_fmac_f32_e32 v5, v6, v3
	v_fma_f32 v2, -v2, v5, v4
	v_div_fmas_f32 v2, v2, v3, v5
	v_div_fixup_f32 v2, v2, v0, 1.0
	v_lshl_add_u64 v[4:5], v[132:133], 1, s[6:7]
	v_lshlrev_b32_e32 v0, 3, v136
	v_lshl_add_u64 v[4:5], v[4:5], 0, v[0:1]
	v_lshl_add_u64 v[4:5], v[4:5], 0, v[0:1]
	v_pk_mul_f32 v[6:7], v[64:65], v[2:3] op_sel_hi:[1,0]
	v_pk_mul_f32 v[8:9], v[66:67], v[2:3] op_sel_hi:[1,0]
	v_pk_mul_f32 v[10:11], v[68:69], v[2:3] op_sel_hi:[1,0]
	v_pk_mul_f32 v[12:13], v[70:71], v[2:3] op_sel_hi:[1,0]
	v_cvt_pk_bf16_f32 v6, v6, v7
	v_cvt_pk_bf16_f32 v7, v8, v9
	v_cvt_pk_bf16_f32 v8, v10, v11
	v_cvt_pk_bf16_f32 v9, v12, v13
	s_nop 1
	v_permlane32_swap_b32_e32 v6, v8
	v_permlane32_swap_b32_e32 v7, v9
	global_store_dwordx4 v[4:5], v[6:9], off
	v_pk_mul_f32 v[84:85], v[72:73], v[2:3] op_sel_hi:[1,0]
	v_pk_mul_f32 v[86:87], v[74:75], v[2:3] op_sel_hi:[1,0]
	v_pk_mul_f32 v[88:89], v[76:77], v[2:3] op_sel_hi:[1,0]
	v_pk_mul_f32 v[90:91], v[78:79], v[2:3] op_sel_hi:[1,0]
	v_cvt_pk_bf16_f32 v84, v84, v85
	v_cvt_pk_bf16_f32 v85, v86, v87
	v_cvt_pk_bf16_f32 v86, v88, v89
	v_cvt_pk_bf16_f32 v87, v90, v91
	s_nop 1
	v_permlane32_swap_b32_e32 v84, v86
	v_permlane32_swap_b32_e32 v85, v87
	global_store_dwordx4 v[4:5], v[84:87], off offset:32
	v_pk_mul_f32 v[6:7], v[48:49], v[2:3] op_sel_hi:[1,0]
	v_pk_mul_f32 v[8:9], v[50:51], v[2:3] op_sel_hi:[1,0]
	v_pk_mul_f32 v[10:11], v[52:53], v[2:3] op_sel_hi:[1,0]
	v_pk_mul_f32 v[12:13], v[54:55], v[2:3] op_sel_hi:[1,0]
	v_cvt_pk_bf16_f32 v6, v6, v7
	v_cvt_pk_bf16_f32 v7, v8, v9
	v_cvt_pk_bf16_f32 v8, v10, v11
	v_cvt_pk_bf16_f32 v9, v12, v13
	s_nop 1
	v_permlane32_swap_b32_e32 v6, v8
	v_permlane32_swap_b32_e32 v7, v9
	global_store_dwordx4 v[4:5], v[6:9], off offset:64
	v_pk_mul_f32 v[84:85], v[56:57], v[2:3] op_sel_hi:[1,0]
	v_pk_mul_f32 v[86:87], v[58:59], v[2:3] op_sel_hi:[1,0]
	v_pk_mul_f32 v[88:89], v[60:61], v[2:3] op_sel_hi:[1,0]
	v_pk_mul_f32 v[90:91], v[62:63], v[2:3] op_sel_hi:[1,0]
	v_cvt_pk_bf16_f32 v84, v84, v85
	v_cvt_pk_bf16_f32 v85, v86, v87
	v_cvt_pk_bf16_f32 v86, v88, v89
	v_cvt_pk_bf16_f32 v87, v90, v91
	s_nop 1
	v_permlane32_swap_b32_e32 v84, v86
	v_permlane32_swap_b32_e32 v85, v87
	global_store_dwordx4 v[4:5], v[84:87], off offset:96
	v_pk_mul_f32 v[6:7], v[32:33], v[2:3] op_sel_hi:[1,0]
	v_pk_mul_f32 v[8:9], v[34:35], v[2:3] op_sel_hi:[1,0]
	v_pk_mul_f32 v[10:11], v[36:37], v[2:3] op_sel_hi:[1,0]
	v_pk_mul_f32 v[12:13], v[38:39], v[2:3] op_sel_hi:[1,0]
	v_cvt_pk_bf16_f32 v6, v6, v7
	v_cvt_pk_bf16_f32 v7, v8, v9
	v_cvt_pk_bf16_f32 v8, v10, v11
	v_cvt_pk_bf16_f32 v9, v12, v13
	s_nop 1
	v_permlane32_swap_b32_e32 v6, v8
	v_permlane32_swap_b32_e32 v7, v9
	global_store_dwordx4 v[4:5], v[6:9], off offset:128
	v_pk_mul_f32 v[84:85], v[40:41], v[2:3] op_sel_hi:[1,0]
	v_pk_mul_f32 v[86:87], v[42:43], v[2:3] op_sel_hi:[1,0]
	v_pk_mul_f32 v[88:89], v[44:45], v[2:3] op_sel_hi:[1,0]
	v_pk_mul_f32 v[90:91], v[46:47], v[2:3] op_sel_hi:[1,0]
	v_cvt_pk_bf16_f32 v84, v84, v85
	v_cvt_pk_bf16_f32 v85, v86, v87
	v_cvt_pk_bf16_f32 v86, v88, v89
	v_cvt_pk_bf16_f32 v87, v90, v91
	s_nop 1
	v_permlane32_swap_b32_e32 v84, v86
	v_permlane32_swap_b32_e32 v85, v87
	global_store_dwordx4 v[4:5], v[84:87], off offset:160
	v_pk_mul_f32 v[6:7], v[16:17], v[2:3] op_sel_hi:[1,0]
	v_pk_mul_f32 v[8:9], v[18:19], v[2:3] op_sel_hi:[1,0]
	v_pk_mul_f32 v[10:11], v[20:21], v[2:3] op_sel_hi:[1,0]
	v_pk_mul_f32 v[12:13], v[22:23], v[2:3] op_sel_hi:[1,0]
	v_cvt_pk_bf16_f32 v6, v6, v7
	v_cvt_pk_bf16_f32 v7, v8, v9
	v_cvt_pk_bf16_f32 v8, v10, v11
	v_cvt_pk_bf16_f32 v9, v12, v13
	s_nop 1
	v_permlane32_swap_b32_e32 v6, v8
	v_permlane32_swap_b32_e32 v7, v9
	global_store_dwordx4 v[4:5], v[6:9], off offset:192
	v_pk_mul_f32 v[84:85], v[24:25], v[2:3] op_sel_hi:[1,0]
	v_pk_mul_f32 v[86:87], v[26:27], v[2:3] op_sel_hi:[1,0]
	v_pk_mul_f32 v[88:89], v[28:29], v[2:3] op_sel_hi:[1,0]
	v_pk_mul_f32 v[90:91], v[30:31], v[2:3] op_sel_hi:[1,0]
	v_cvt_pk_bf16_f32 v84, v84, v85
	v_cvt_pk_bf16_f32 v85, v86, v87
	v_cvt_pk_bf16_f32 v86, v88, v89
	v_cvt_pk_bf16_f32 v87, v90, v91
	s_nop 1
	v_permlane32_swap_b32_e32 v84, v86
	v_permlane32_swap_b32_e32 v85, v87
	global_store_dwordx4 v[4:5], v[84:87], off offset:224
	s_cbranch_scc1 .LBB0_147

; #define MFMA32(a, b, c) __builtin_amdgcn_mfma_f32_32x32x16_bf16((a), (b), (c), 0, 0, 0)
; DI unsigned pk2(float lo, float hi) { return cvtpk(lo, hi); }
; template <int PH>
; DI void gla_unit(LAS char* lds, int unit, const bf16* PROJ, const float* W2, const float* gb, bf16* SC, float* DEC, const float* cnorm, bf16* MIXED, bf16* QG, bf16* KG) {
;     ...
;         for (int tile = w; tile < 18; tile += 8) { const int mi = tile / 6, ni = tile - 6 * mi;
;             f32x16 c;
; #pragma unroll
;             for (int r = 0; r < 16; ++r) c[r] = 0.f;
; #pragma unroll
;             for (int s = 0; s < 4; ++s) { const bf16x8 a = frag_tr(lds + G_KT, PQK, 16 * s, 32 * mi, lane), bq = frag_tr(lds + G_VT, PV, 16 * s, 32 * ni, lane); c = MFMA32(a, bq, c); }
; #pragma unroll
;             for (int g = 0; g < 4; ++g) { u32x2 o; o.x = pk2(c[4 * g], c[4 * g + 1]); o.y = pk2(c[4 * g + 2], c[4 * g + 3]);
;                 *(u32x2*)(dst + (32 * ni + r32) * 96 + 32 * mi + 8 * g + 4 * hi) = o; } }
.LBB0_497:
	s_mul_hi_i32 s10, s7, 0x2aaaaaab
	s_lshr_b32 s11, s10, 31
	s_add_i32 s10, s10, s11
	s_mul_i32 s11, s10, 0xfffffe80
	v_lshl_add_u32 v27, s10, 6, v20
	v_add_u32_e32 v36, s11, v26
	v_add_u32_e32 v4, v27, v21
	v_add_u32_e32 v6, 0xffffaec0, v36
	v_add_u32_e32 v8, 0xffffb500, v36
	ds_read_b64_tr_b16 v[2:3], v4 offset:62464
	ds_read_b64_tr_b16 v[4:5], v4 offset:63296
	ds_read_b64_tr_b16 v[6:7], v6
	ds_read_b64_tr_b16 v[8:9], v8
	s_waitcnt lgkmcnt(0)
	v_mfma_f32_32x32x16_bf16 v[2:17], v[2:5], v[6:9], 0
	v_add_u32_e32 v30, v27, v22
	v_add_u32_e32 v32, 0xffffc7c0, v36
	v_add_u32_e32 v34, 0xffffce00, v36
	ds_read_b64_tr_b16 v[28:29], v30 offset:62464
	ds_read_b64_tr_b16 v[30:31], v30 offset:63296
	ds_read_b64_tr_b16 v[32:33], v32
	ds_read_b64_tr_b16 v[34:35], v34
	s_mul_i32 s11, s10, 0xffffb800
	s_waitcnt lgkmcnt(0)
	v_mfma_f32_32x32x16_bf16 v[2:17], v[28:31], v[32:35], v[2:17]
	v_add_u32_e32 v30, v27, v23
	v_add_u32_e32 v32, 0xffffe0c0, v36
	v_add_u32_e32 v34, 0xffffe700, v36
	ds_read_b64_tr_b16 v[28:29], v30 offset:62464
	ds_read_b64_tr_b16 v[30:31], v30 offset:63296
	ds_read_b64_tr_b16 v[32:33], v32
	ds_read_b64_tr_b16 v[34:35], v34
	v_add_u32_e32 v27, v27, v24
	s_waitcnt lgkmcnt(0)
	v_mfma_f32_32x32x16_bf16 v[2:17], v[28:31], v[32:35], v[2:17]
	ds_read_b64_tr_b16 v[28:29], v27 offset:62464
	ds_read_b64_tr_b16 v[30:31], v27 offset:63296
	v_add_u32_e32 v27, 0xfffff9c0, v36
	ds_read_b64_tr_b16 v[32:33], v27
	ds_read_b64_tr_b16 v[34:35], v36
	s_lshl_b32 s10, s10, 5
	v_add_u32_e32 v26, 0x200, v26
	s_waitcnt lgkmcnt(0)
	v_mfma_f32_32x32x16_bf16 v[2:17], v[28:31], v[32:35], v[2:17]
	v_add_u32_e32 v28, s11, v25
	v_ashrrev_i32_e32 v29, 31, v28
	v_lshl_add_u64 v[28:29], v[28:29], 1, v[18:19]
	s_ashr_i32 s11, s10, 31
	v_lshl_add_u64 v[28:29], s[10:11], 1, v[28:29]
	v_lshl_add_u64 v[28:29], v[28:29], 0, v[0:1]
	v_lshl_add_u64 v[28:29], v[28:29], 0, v[0:1]
	s_add_i32 s10, s7, 8
	s_nop 4
	v_cvt_pk_bf16_f32 v2, v2, v3
	v_cvt_pk_bf16_f32 v3, v4, v5
	v_cvt_pk_bf16_f32 v4, v6, v7
	v_cvt_pk_bf16_f32 v5, v8, v9
	v_cvt_pk_bf16_f32 v10, v10, v11
	v_cvt_pk_bf16_f32 v11, v12, v13
	v_cvt_pk_bf16_f32 v12, v14, v15
	v_cvt_pk_bf16_f32 v13, v16, v17
	v_add_u32_e32 v25, 0x6000, v25
	s_cmp_lt_i32 s7, 10
	s_mov_b32 s7, s10
	v_permlane32_swap_b32_e32 v2, v4
	v_permlane32_swap_b32_e32 v3, v5
	v_permlane32_swap_b32_e32 v10, v12
	v_permlane32_swap_b32_e32 v11, v13
	global_store_dwordx4 v[28:29], v[2:5], off
	global_store_dwordx4 v[28:29], v[10:13], off offset:32
	s_cbranch_scc1 .LBB0_497
	s_branch .LBB0_488

; DI unsigned cvtpk(float lo, float hi) { f32x2_t v = {lo, hi}; bf16x2_t b = __builtin_convertvector(v, bf16x2_t); return __builtin_bit_cast(unsigned, b); }
; DI void dil_compute(LAS char* lds, const DilU& u, const LAS float* tbl, int tid, const bf16x8 (&qf)[4]) {
;     ...
;     bf16* orow = u.Ob + (long)(32 * w + r32) * u.ostride;
; #pragma unroll
;     for (int db = 0; db < 2; ++db)
; #pragma unroll
;         for (int g = 0; g < 4; ++g) { u32x2 wv; wv.x = cvtpk(o[db][4 * g] * inv, o[db][4 * g + 1] * inv); wv.y = cvtpk(o[db][4 * g + 2] * inv, o[db][4 * g + 3] * inv);
;             *(u32x2*)(orow + 32 * db + 8 * g + 4 * hi) = wv; }
; __global__ void __launch_bounds__(NTHR, 2) fwd_mega(Args args) {
;     ...
;                     __syncthreads();
;                     if (has_next) { DIL_MAKE(nxt, u + G); DIL_GLOAD(nxt, RG); }
;                     dil_compute(lds, cur, DIL_TBLP(u), tid, qf);
;                     asm volatile("s_waitcnt lgkmcnt(0)\n\ts_barrier" ::: "memory");
;                     cur = nxt; ++it;
;                 }
.LBB0_521:
	s_or_b64 exec, exec, s[10:11]
	s_waitcnt lgkmcnt(0)
	s_barrier
	v_readlane_b32 s100, v254, 29
	v_lshrrev_b32_e32 v172, 3, v131
	v_and_b32_e32 v173, 7, v131
	v_lshl_add_u32 v172, v172, 6, v173
	s_lshl_b32 s101, s100, 3
	v_add_u32_e32 v172, s101, v172
	v_mul_u32_u24_e32 v172, 0x90, v172
	v_lshrrev_b32_e32 v173, 5, v226
	v_lshl_add_u32 v172, v173, 4, v172
	ds_write_b128 v172, v[18:21]
	ds_write_b128 v172, v[26:29] offset:32
	ds_write_b128 v172, v[2:5] offset:64
	ds_write_b128 v172, v[10:13] offset:96
	ds_read_b128 v[184:187], v141
	ds_read_b128 v[188:191], v143
	ds_read_b128 v[192:195], v148
	ds_read_b128 v[196:199], v149
	s_lshl_b32 s100, s100, 5
	v_lshrrev_b32_e32 v173, 3, v226
	v_add_u32_e32 v173, s100, v173
	v_mul_lo_u32 v174, v173, s6
	v_mov_b32_e32 v175, 0
	v_lshl_add_u64 v[174:175], v[174:175], 1, s[12:13]
	v_and_b32_e32 v176, 7, v226
	v_lshlrev_b32_e32 v176, 4, v176
	v_mov_b32_e32 v177, 0
	v_lshl_add_u64 v[174:175], v[174:175], 0, v[176:177]
	s_lshl_b32 s98, s6, 4
	s_mov_b32 s99, 0
	s_waitcnt lgkmcnt(3)
	global_store_dwordx4 v[174:175], v[184:187], off
	v_lshl_add_u64 v[174:175], v[174:175], 0, s[98:99]
	s_waitcnt lgkmcnt(2)
	global_store_dwordx4 v[174:175], v[188:191], off
	v_lshl_add_u64 v[174:175], v[174:175], 0, s[98:99]
	s_waitcnt lgkmcnt(1)
	global_store_dwordx4 v[174:175], v[192:195], off
	v_lshl_add_u64 v[174:175], v[174:175], 0, s[98:99]
	s_waitcnt lgkmcnt(0)
	global_store_dwordx4 v[174:175], v[196:199], off
	s_waitcnt vmcnt(4)
	v_mov_b64_e32 v[98:99], v[126:127]
	s_waitcnt vmcnt(4)
	v_mov_b64_e32 v[102:103], v[122:123]
	s_waitcnt vmcnt(4)
	v_mov_b64_e32 v[106:107], v[118:119]
	s_waitcnt vmcnt(4)
	v_mov_b64_e32 v[110:111], v[114:115]
	s_and_b64 vcc, exec, s[14:15]
	v_mov_b64_e32 v[100:101], v[128:129]
	v_mov_b64_e32 v[104:105], v[124:125]
	v_mov_b64_e32 v[108:109], v[120:121]
	v_mov_b64_e32 v[112:113], v[116:117]
	s_mov_b32 s20, s7
	s_mov_b64 s[12:13], s[16:17]
	s_mov_b64 s[8:9], s[22:23]
	s_mov_b32 s6, s26
	s_mov_b32 s5, s27
	s_mov_b32 s4, s21
	s_cbranch_vccnz .LBB0_546

; #define MFMA32(a, b, c) __builtin_amdgcn_mfma_f32_32x32x16_bf16((a), (b), (c), 0, 0, 0)
; DI bf16x8 pack8(const f32x16& x, int s) { u32x4 p; p[0] = cvtpk(x[8 * s], x[8 * s + 1]); p[1] = cvtpk(x[8 * s + 2], x[8 * s + 3]); p[2] = cvtpk(x[8 * s + 4], x[8 * s + 5]); p[3] = cvtpk(x[8 * s + 6], x[8 * s + 7]); return __builtin_bit_cast(bf16x8, p); }
; DI void dil_compute(LAS char* lds, const DilU& u, const LAS float* tbl, int tid, const bf16x8 (&qf)[4]) {
;     ...
;         float mx = p[0];
; #pragma unroll
;         for (int r = 1; r < 16; ++r) mx = fmaxf(mx, p[r]);
;         mx = fmaxf(mx, __shfl_xor(mx, 32));
;         const float mn = fmaxf(m, mx);
;         if (__any(mn > m)) {
;             const float mr_ = (mn == -INFINITY) ? 0.f : mn;
;             const float alpha = __builtin_amdgcn_exp2f(m - mr_);
;             l *= alpha;
; #pragma unroll
;             for (int i = 0; i < 2; ++i)
; #pragma unroll
;                 for (int r = 0; r < 16; ++r) o[i][r] *= alpha;
;             m = mn;
;         }
;         const float mref = (m == -INFINITY) ? 0.f : m;
; #pragma unroll
;         for (int r = 0; r < 16; ++r) { p[r] = __builtin_amdgcn_exp2f(p[r] - mref); l += p[r]; }
;         const bf16x8 pb0 = pack8(p, 0), pb1 = pack8(p, 1);
; #pragma unroll
;         for (int db = 0; db < 2; ++db) {
;             const bf16x8 v0 = frag_tr_perm(Vt, DIL_PITCH, 0, 32 * db, lane), v1 = frag_tr_perm(Vt, DIL_PITCH, 16, 32 * db, lane);
;             o[db] = MFMA32(v0, pb0, o[db]); o[db] = MFMA32(v1, pb1, o[db]);
;         }
.Ldil_nomask:
	v_max3_f32 v145, v170, v171, v220
	v_max3_f32 v145, v145, v221, v223
	ds_bpermute_b32 v222, v133, v145
	v_mov_b32_e32 v221, 0xff800000
	s_waitcnt lgkmcnt(0)
	v_max_f32_e32 v145, v145, v222
	v_cmp_neq_f32_e32 vcc, v145, v221
	s_nop 1
	v_cndmask_b32_e32 v170, 0, v145, vcc
	v_sub_f32_e32 v172, v172, v170
	v_sub_f32_e32 v173, v173, v170
	v_sub_f32_e32 v174, v174, v170
	v_sub_f32_e32 v175, v175, v170
	v_sub_f32_e32 v176, v176, v170
	v_sub_f32_e32 v177, v177, v170
	v_sub_f32_e32 v178, v178, v170
	v_sub_f32_e32 v179, v179, v170
	v_sub_f32_e32 v180, v180, v170
	v_sub_f32_e32 v181, v181, v170
	v_sub_f32_e32 v182, v182, v170
	v_sub_f32_e32 v183, v183, v170
	v_sub_f32_e32 v184, v184, v170
	v_sub_f32_e32 v185, v185, v170
	v_sub_f32_e32 v186, v186, v170
	v_sub_f32_e32 v187, v187, v170
	v_exp_f32_e32 v172, v172
	v_exp_f32_e32 v173, v173
	v_exp_f32_e32 v174, v174
	v_exp_f32_e32 v175, v175
	v_exp_f32_e32 v176, v176
	v_exp_f32_e32 v177, v177
	v_exp_f32_e32 v178, v178
	v_exp_f32_e32 v179, v179
	v_exp_f32_e32 v180, v180
	v_exp_f32_e32 v181, v181
	v_exp_f32_e32 v182, v182
	v_exp_f32_e32 v183, v183
	v_exp_f32_e32 v184, v184
	v_exp_f32_e32 v185, v185
	v_exp_f32_e32 v186, v186
	v_exp_f32_e32 v187, v187
	v_add_f32_e32 v171, v172, v174
	v_add_f32_e32 v220, v173, v175
	v_add_f32_e32 v171, v171, v176
	v_add_f32_e32 v220, v220, v177
	v_add_f32_e32 v171, v171, v178
	v_add_f32_e32 v220, v220, v179
	v_add_f32_e32 v171, v171, v180
	v_add_f32_e32 v220, v220, v181
	v_add_f32_e32 v171, v171, v182
	v_add_f32_e32 v220, v220, v183
	v_add_f32_e32 v171, v171, v184
	v_add_f32_e32 v220, v220, v185
	v_add_f32_e32 v171, v171, v186
	v_add_f32_e32 v220, v220, v187
	v_cvt_pk_bf16_f32 v98, v172, v173
	v_cvt_pk_bf16_f32 v99, v174, v175
	v_cvt_pk_bf16_f32 v100, v176, v177
	v_cvt_pk_bf16_f32 v101, v178, v179
	v_cvt_pk_bf16_f32 v102, v180, v181
	v_cvt_pk_bf16_f32 v103, v182, v183
	v_cvt_pk_bf16_f32 v104, v184, v185
	v_cvt_pk_bf16_f32 v105, v186, v187
	v_add_u32_e32 v222, 0, v153
	ds_read_b64_tr_b16 v[172:173], v222 offset:55296
	ds_read_b64_tr_b16 v[174:175], v222 offset:56448
	ds_read_b64_tr_b16 v[176:177], v222 offset:57600
	ds_read_b64_tr_b16 v[178:179], v222 offset:58752
	ds_read_b64_tr_b16 v[180:181], v222 offset:55360
	ds_read_b64_tr_b16 v[182:183], v222 offset:56512
	ds_read_b64_tr_b16 v[184:185], v222 offset:57664
	ds_read_b64_tr_b16 v[186:187], v222 offset:58816
	v_sub_f32_e32 v188, v188, v170
	v_sub_f32_e32 v189, v189, v170
	v_sub_f32_e32 v190, v190, v170
	v_sub_f32_e32 v191, v191, v170
	v_sub_f32_e32 v192, v192, v170
	v_sub_f32_e32 v193, v193, v170
	v_sub_f32_e32 v194, v194, v170
	v_sub_f32_e32 v195, v195, v170
	v_sub_f32_e32 v196, v196, v170
	v_sub_f32_e32 v197, v197, v170
	v_sub_f32_e32 v198, v198, v170
	v_sub_f32_e32 v199, v199, v170
	v_sub_f32_e32 v200, v200, v170
	v_sub_f32_e32 v201, v201, v170
	v_sub_f32_e32 v202, v202, v170
	v_sub_f32_e32 v203, v203, v170
	v_exp_f32_e32 v188, v188
	v_exp_f32_e32 v189, v189
	v_exp_f32_e32 v190, v190
	v_exp_f32_e32 v191, v191
	v_exp_f32_e32 v192, v192
	v_exp_f32_e32 v193, v193
	v_exp_f32_e32 v194, v194
	v_exp_f32_e32 v195, v195
	v_exp_f32_e32 v196, v196
	v_exp_f32_e32 v197, v197
	v_exp_f32_e32 v198, v198
	v_exp_f32_e32 v199, v199
	v_exp_f32_e32 v200, v200
	v_exp_f32_e32 v201, v201
	v_exp_f32_e32 v202, v202
	v_exp_f32_e32 v203, v203
	v_add_f32_e32 v171, v171, v188
	v_add_f32_e32 v220, v220, v189
	v_add_f32_e32 v171, v171, v190
	v_add_f32_e32 v220, v220, v191
	v_add_f32_e32 v171, v171, v192
	v_add_f32_e32 v220, v220, v193
	v_add_f32_e32 v171, v171, v194
	v_add_f32_e32 v220, v220, v195
	v_add_f32_e32 v171, v171, v196
	v_add_f32_e32 v220, v220, v197
	v_add_f32_e32 v171, v171, v198
	v_add_f32_e32 v220, v220, v199
	v_add_f32_e32 v171, v171, v200
	v_add_f32_e32 v220, v220, v201
	v_add_f32_e32 v171, v171, v202
	v_add_f32_e32 v220, v220, v203
	v_cvt_pk_bf16_f32 v106, v188, v189
	v_cvt_pk_bf16_f32 v107, v190, v191
	v_cvt_pk_bf16_f32 v108, v192, v193
	v_cvt_pk_bf16_f32 v109, v194, v195
	v_cvt_pk_bf16_f32 v110, v196, v197
	v_cvt_pk_bf16_f32 v111, v198, v199
	v_cvt_pk_bf16_f32 v112, v200, v201
	v_cvt_pk_bf16_f32 v113, v202, v203
	s_waitcnt lgkmcnt(6)
	v_mfma_f32_32x32x16_bf16 v[18:33], v[172:175], v[98:101], 0
	s_waitcnt lgkmcnt(4)
	v_mfma_f32_32x32x16_bf16 v[18:33], v[176:179], v[102:105], v[18:33]
	s_waitcnt lgkmcnt(2)
	v_mfma_f32_32x32x16_bf16 v[2:17], v[180:183], v[98:101], 0
	s_waitcnt lgkmcnt(0)
	v_mfma_f32_32x32x16_bf16 v[2:17], v[184:187], v[102:105], v[2:17]
	v_add_u32_e32 v222, 4608, v153
	ds_read_b64_tr_b16 v[188:189], v222 offset:55296
	ds_read_b64_tr_b16 v[190:191], v222 offset:56448
	ds_read_b64_tr_b16 v[192:193], v222 offset:57600
	ds_read_b64_tr_b16 v[194:195], v222 offset:58752
	ds_read_b64_tr_b16 v[196:197], v222 offset:55360
	ds_read_b64_tr_b16 v[198:199], v222 offset:56512
	ds_read_b64_tr_b16 v[200:201], v222 offset:57664
	ds_read_b64_tr_b16 v[202:203], v222 offset:58816
	v_sub_f32_e32 v204, v204, v170
	v_sub_f32_e32 v205, v205, v170
	v_sub_f32_e32 v206, v206, v170
	v_sub_f32_e32 v207, v207, v170
	v_sub_f32_e32 v208, v208, v170
	v_sub_f32_e32 v209, v209, v170
	v_sub_f32_e32 v210, v210, v170
	v_sub_f32_e32 v211, v211, v170
	v_sub_f32_e32 v212, v212, v170
	v_sub_f32_e32 v213, v213, v170
	v_sub_f32_e32 v214, v214, v170
	v_sub_f32_e32 v215, v215, v170
	v_sub_f32_e32 v216, v216, v170
	v_sub_f32_e32 v217, v217, v170
	v_sub_f32_e32 v218, v218, v170
	v_sub_f32_e32 v219, v219, v170
	v_exp_f32_e32 v204, v204
	v_exp_f32_e32 v205, v205
	v_exp_f32_e32 v206, v206
	v_exp_f32_e32 v207, v207
	v_exp_f32_e32 v208, v208
	v_exp_f32_e32 v209, v209
	v_exp_f32_e32 v210, v210
	v_exp_f32_e32 v211, v211
	v_exp_f32_e32 v212, v212
	v_exp_f32_e32 v213, v213
	v_exp_f32_e32 v214, v214
	v_exp_f32_e32 v215, v215
	v_exp_f32_e32 v216, v216
	v_exp_f32_e32 v217, v217
	v_exp_f32_e32 v218, v218
	v_exp_f32_e32 v219, v219
	v_add_f32_e32 v171, v171, v204
	v_add_f32_e32 v220, v220, v205
	v_add_f32_e32 v171, v171, v206
	v_add_f32_e32 v220, v220, v207
	v_add_f32_e32 v171, v171, v208
	v_add_f32_e32 v220, v220, v209
	v_add_f32_e32 v171, v171, v210
	v_add_f32_e32 v220, v220, v211
	v_add_f32_e32 v171, v171, v212
	v_add_f32_e32 v220, v220, v213
	v_add_f32_e32 v171, v171, v214
	v_add_f32_e32 v220, v220, v215
	v_add_f32_e32 v171, v171, v216
	v_add_f32_e32 v220, v220, v217
	v_add_f32_e32 v171, v171, v218
	v_add_f32_e32 v220, v220, v219
	v_cvt_pk_bf16_f32 v98, v204, v205
	v_cvt_pk_bf16_f32 v99, v206, v207
	v_cvt_pk_bf16_f32 v100, v208, v209
	v_cvt_pk_bf16_f32 v101, v210, v211
	v_cvt_pk_bf16_f32 v102, v212, v213
	v_cvt_pk_bf16_f32 v103, v214, v215
	v_cvt_pk_bf16_f32 v104, v216, v217
	v_cvt_pk_bf16_f32 v105, v218, v219
	s_waitcnt lgkmcnt(6)
; #define MFMA32(a, b, c) __builtin_amdgcn_mfma_f32_32x32x16_bf16((a), (b), (c), 0, 0, 0)
; DI bf16x8 pack8(const f32x16& x, int s) { u32x4 p; p[0] = cvtpk(x[8 * s], x[8 * s + 1]); p[1] = cvtpk(x[8 * s + 2], x[8 * s + 3]); p[2] = cvtpk(x[8 * s + 4], x[8 * s + 5]); p[3] = cvtpk(x[8 * s + 6], x[8 * s + 7]); return __builtin_bit_cast(bf16x8, p); }
; DI void dil_compute(LAS char* lds, const DilU& u, const LAS float* tbl, int tid, const bf16x8 (&qf)[4]) {
;     ...
;         const float mref = (m == -INFINITY) ? 0.f : m;
; #pragma unroll
;         for (int r = 0; r < 16; ++r) { p[r] = __builtin_amdgcn_exp2f(p[r] - mref); l += p[r]; }
;         const bf16x8 pb0 = pack8(p, 0), pb1 = pack8(p, 1);
; #pragma unroll
;         for (int db = 0; db < 2; ++db) {
;             const bf16x8 v0 = frag_tr_perm(Vt, DIL_PITCH, 0, 32 * db, lane), v1 = frag_tr_perm(Vt, DIL_PITCH, 16, 32 * db, lane);
;             o[db] = MFMA32(v0, pb0, o[db]); o[db] = MFMA32(v1, pb1, o[db]);
;         }
	v_mfma_f32_32x32x16_bf16 v[18:33], v[188:191], v[106:109], v[18:33]
	s_waitcnt lgkmcnt(4)
	v_mfma_f32_32x32x16_bf16 v[18:33], v[192:195], v[110:113], v[18:33]
	s_waitcnt lgkmcnt(2)
	v_mfma_f32_32x32x16_bf16 v[2:17], v[196:199], v[106:109], v[2:17]
	s_waitcnt lgkmcnt(0)
	v_mfma_f32_32x32x16_bf16 v[2:17], v[200:203], v[110:113], v[2:17]
	v_add_u32_e32 v222, 9216, v153
	ds_read_b64_tr_b16 v[204:205], v222 offset:55296
	ds_read_b64_tr_b16 v[206:207], v222 offset:56448
	ds_read_b64_tr_b16 v[208:209], v222 offset:57600
	ds_read_b64_tr_b16 v[210:211], v222 offset:58752
	ds_read_b64_tr_b16 v[212:213], v222 offset:55360
	ds_read_b64_tr_b16 v[214:215], v222 offset:56512
	ds_read_b64_tr_b16 v[216:217], v222 offset:57664
	ds_read_b64_tr_b16 v[218:219], v222 offset:58816
	v_sub_f32_e32 v154, v154, v170
	v_sub_f32_e32 v155, v155, v170
	v_sub_f32_e32 v156, v156, v170
	v_sub_f32_e32 v157, v157, v170
	v_sub_f32_e32 v158, v158, v170
	v_sub_f32_e32 v159, v159, v170
	v_sub_f32_e32 v160, v160, v170
	v_sub_f32_e32 v161, v161, v170
	v_sub_f32_e32 v162, v162, v170
	v_sub_f32_e32 v163, v163, v170
	v_sub_f32_e32 v164, v164, v170
	v_sub_f32_e32 v165, v165, v170
	v_sub_f32_e32 v166, v166, v170
	v_sub_f32_e32 v167, v167, v170
	v_sub_f32_e32 v168, v168, v170
	v_sub_f32_e32 v169, v169, v170
	v_exp_f32_e32 v154, v154
	v_exp_f32_e32 v155, v155
	v_exp_f32_e32 v156, v156
	v_exp_f32_e32 v157, v157
	v_exp_f32_e32 v158, v158
	v_exp_f32_e32 v159, v159
	v_exp_f32_e32 v160, v160
	v_exp_f32_e32 v161, v161
	v_exp_f32_e32 v162, v162
	v_exp_f32_e32 v163, v163
	v_exp_f32_e32 v164, v164
	v_exp_f32_e32 v165, v165
	v_exp_f32_e32 v166, v166
	v_exp_f32_e32 v167, v167
	v_exp_f32_e32 v168, v168
	v_exp_f32_e32 v169, v169
	v_add_f32_e32 v171, v171, v154
	v_add_f32_e32 v220, v220, v155
	v_add_f32_e32 v171, v171, v156
	v_add_f32_e32 v220, v220, v157
	v_add_f32_e32 v171, v171, v158
	v_add_f32_e32 v220, v220, v159
	v_add_f32_e32 v171, v171, v160
	v_add_f32_e32 v220, v220, v161
	v_add_f32_e32 v171, v171, v162
	v_add_f32_e32 v220, v220, v163
	v_add_f32_e32 v171, v171, v164
	v_add_f32_e32 v220, v220, v165
	v_add_f32_e32 v171, v171, v166
	v_add_f32_e32 v220, v220, v167
	v_add_f32_e32 v171, v171, v168
	v_add_f32_e32 v220, v220, v169
	v_cvt_pk_bf16_f32 v106, v154, v155
	v_cvt_pk_bf16_f32 v107, v156, v157
	v_cvt_pk_bf16_f32 v108, v158, v159
	v_cvt_pk_bf16_f32 v109, v160, v161
	v_cvt_pk_bf16_f32 v110, v162, v163
	v_cvt_pk_bf16_f32 v111, v164, v165
	v_cvt_pk_bf16_f32 v112, v166, v167
	v_cvt_pk_bf16_f32 v113, v168, v169
	s_waitcnt lgkmcnt(6)
	v_mfma_f32_32x32x16_bf16 v[18:33], v[204:207], v[98:101], v[18:33]
	s_waitcnt lgkmcnt(4)
	v_mfma_f32_32x32x16_bf16 v[18:33], v[208:211], v[102:105], v[18:33]
	s_waitcnt lgkmcnt(2)
	v_mfma_f32_32x32x16_bf16 v[2:17], v[212:215], v[98:101], v[2:17]
	s_waitcnt lgkmcnt(0)
	v_mfma_f32_32x32x16_bf16 v[2:17], v[216:219], v[102:105], v[2:17]
	v_add_u32_e32 v222, 13824, v153
	ds_read_b64_tr_b16 v[154:155], v222 offset:55296
	ds_read_b64_tr_b16 v[156:157], v222 offset:56448
	ds_read_b64_tr_b16 v[158:159], v222 offset:57600
	ds_read_b64_tr_b16 v[160:161], v222 offset:58752
	ds_read_b64_tr_b16 v[162:163], v222 offset:55360
	ds_read_b64_tr_b16 v[164:165], v222 offset:56512
	ds_read_b64_tr_b16 v[166:167], v222 offset:57664
	ds_read_b64_tr_b16 v[168:169], v222 offset:58816
	v_sub_f32_e32 v34, v34, v170
	v_sub_f32_e32 v35, v35, v170
	v_sub_f32_e32 v36, v36, v170
	v_sub_f32_e32 v37, v37, v170
	v_sub_f32_e32 v38, v38, v170
	v_sub_f32_e32 v39, v39, v170
	v_sub_f32_e32 v40, v40, v170
	v_sub_f32_e32 v41, v41, v170
	v_sub_f32_e32 v42, v42, v170
	v_sub_f32_e32 v43, v43, v170
	v_sub_f32_e32 v44, v44, v170
	v_sub_f32_e32 v45, v45, v170
	v_sub_f32_e32 v46, v46, v170
	v_sub_f32_e32 v47, v47, v170
	v_sub_f32_e32 v48, v48, v170
	v_sub_f32_e32 v49, v49, v170
	v_exp_f32_e32 v34, v34
	v_exp_f32_e32 v35, v35
	v_exp_f32_e32 v36, v36
	v_exp_f32_e32 v37, v37
	v_exp_f32_e32 v38, v38
	v_exp_f32_e32 v39, v39
	v_exp_f32_e32 v40, v40
	v_exp_f32_e32 v41, v41
	v_exp_f32_e32 v42, v42
	v_exp_f32_e32 v43, v43
	v_exp_f32_e32 v44, v44
	v_exp_f32_e32 v45, v45
	v_exp_f32_e32 v46, v46
	v_exp_f32_e32 v47, v47
	v_exp_f32_e32 v48, v48
	v_exp_f32_e32 v49, v49
	v_add_f32_e32 v171, v171, v34
	v_add_f32_e32 v220, v220, v35
	v_add_f32_e32 v171, v171, v36
	v_add_f32_e32 v220, v220, v37
	v_add_f32_e32 v171, v171, v38
	v_add_f32_e32 v220, v220, v39
	v_add_f32_e32 v171, v171, v40
	v_add_f32_e32 v220, v220, v41
	v_add_f32_e32 v171, v171, v42
	v_add_f32_e32 v220, v220, v43
	v_add_f32_e32 v171, v171, v44
	v_add_f32_e32 v220, v220, v45
	v_add_f32_e32 v171, v171, v46
	v_add_f32_e32 v220, v220, v47
	v_add_f32_e32 v171, v171, v48
	v_add_f32_e32 v220, v220, v49
	v_cvt_pk_bf16_f32 v98, v34, v35
	v_cvt_pk_bf16_f32 v99, v36, v37
	v_cvt_pk_bf16_f32 v100, v38, v39
	v_cvt_pk_bf16_f32 v101, v40, v41
	v_cvt_pk_bf16_f32 v102, v42, v43
	v_cvt_pk_bf16_f32 v103, v44, v45
	v_cvt_pk_bf16_f32 v104, v46, v47
	v_cvt_pk_bf16_f32 v105, v48, v49
	s_waitcnt lgkmcnt(6)
; #define MFMA32(a, b, c) __builtin_amdgcn_mfma_f32_32x32x16_bf16((a), (b), (c), 0, 0, 0)
; DI unsigned cvtpk(float lo, float hi) { f32x2_t v = {lo, hi}; bf16x2_t b = __builtin_convertvector(v, bf16x2_t); return __builtin_bit_cast(unsigned, b); }
; DI void dil_compute(LAS char* lds, const DilU& u, const LAS float* tbl, int tid, const bf16x8 (&qf)[4]) {
;     ...
;         for (int db = 0; db < 2; ++db) {
;             const bf16x8 v0 = frag_tr_perm(Vt, DIL_PITCH, 0, 32 * db, lane), v1 = frag_tr_perm(Vt, DIL_PITCH, 16, 32 * db, lane);
;             o[db] = MFMA32(v0, pb0, o[db]); o[db] = MFMA32(v1, pb1, o[db]);
;         }
;     }
;     l += __shfl_xor(l, 32);
;     const float inv = 1.f / l;
;     bf16* orow = u.Ob + (long)(32 * w + r32) * u.ostride;
; #pragma unroll
;     for (int db = 0; db < 2; ++db)
; #pragma unroll
;         for (int g = 0; g < 4; ++g) { u32x2 wv; wv.x = cvtpk(o[db][4 * g] * inv, o[db][4 * g + 1] * inv); wv.y = cvtpk(o[db][4 * g + 2] * inv, o[db][4 * g + 3] * inv);
;             *(u32x2*)(orow + 32 * db + 8 * g + 4 * hi) = wv; }
;     if (hi == 0) u.lse[(long)(32 * w + r32) * u.lstride] = m + __log2f(l);
	v_mfma_f32_32x32x16_bf16 v[18:33], v[154:157], v[106:109], v[18:33]
	s_waitcnt lgkmcnt(4)
	v_mfma_f32_32x32x16_bf16 v[18:33], v[158:161], v[110:113], v[18:33]
	s_waitcnt lgkmcnt(2)
	v_mfma_f32_32x32x16_bf16 v[2:17], v[162:165], v[106:109], v[2:17]
	s_waitcnt lgkmcnt(0)
	v_mfma_f32_32x32x16_bf16 v[2:17], v[166:169], v[110:113], v[2:17]
	v_add_u32_e32 v222, 18432, v153
	ds_read_b64_tr_b16 v[34:35], v222 offset:55296
	ds_read_b64_tr_b16 v[36:37], v222 offset:56448
	ds_read_b64_tr_b16 v[38:39], v222 offset:57600
	ds_read_b64_tr_b16 v[40:41], v222 offset:58752
	ds_read_b64_tr_b16 v[42:43], v222 offset:55360
	ds_read_b64_tr_b16 v[44:45], v222 offset:56512
	ds_read_b64_tr_b16 v[46:47], v222 offset:57664
	ds_read_b64_tr_b16 v[48:49], v222 offset:58816
	s_waitcnt lgkmcnt(6)
	v_mfma_f32_32x32x16_bf16 v[18:33], v[34:37], v[98:101], v[18:33]
	s_waitcnt lgkmcnt(4)
	v_mfma_f32_32x32x16_bf16 v[18:33], v[38:41], v[102:105], v[18:33]
	s_waitcnt lgkmcnt(2)
	v_mfma_f32_32x32x16_bf16 v[2:17], v[42:45], v[98:101], v[2:17]
	s_waitcnt lgkmcnt(0)
	v_mfma_f32_32x32x16_bf16 v[2:17], v[46:49], v[102:105], v[2:17]
	v_add_f32_e32 v174, v171, v220
	v_or_b32_e32 v172, s10, v131
	ds_bpermute_b32 v173, v133, v174
	v_mov_b32_e32 v147, 0
	v_mul_lo_u32 v178, v172, s6
	v_mov_b32_e32 v179, 0
	v_lshl_add_u64 v[178:179], v[178:179], 1, s[12:13]
	v_lshl_add_u64 v[178:179], v[178:179], 0, v[146:147]
	s_waitcnt lgkmcnt(0)
	v_add_f32_e32 v174, v174, v173
	v_div_scale_f32 v175, s[10:11], v174, v174, 1.0
	v_rcp_f32_e32 v176, v175
	v_div_scale_f32 v177, vcc, 1.0, v174, 1.0
	v_fma_f32 v180, -v175, v176, 1.0
	v_fmac_f32_e32 v176, v180, v176
	v_mul_f32_e32 v180, v177, v176
	v_fma_f32 v181, -v175, v180, v177
	v_fmac_f32_e32 v180, v181, v176
	v_fma_f32 v175, -v175, v180, v177
	v_div_fmas_f32 v175, v175, v176, v180
	v_div_fixup_f32 v176, v175, v174, 1.0
	s_nop 0
	v_lshl_add_u64 v[178:179], v[178:179], 0, v[146:147]
	v_mul_f32_e32 v18, v18, v176
	v_mul_f32_e32 v19, v19, v176
	v_mul_f32_e32 v20, v20, v176
	v_mul_f32_e32 v21, v21, v176
	v_mul_f32_e32 v22, v22, v176
	v_mul_f32_e32 v23, v23, v176
	v_mul_f32_e32 v24, v24, v176
	v_mul_f32_e32 v25, v25, v176
	v_cvt_pk_bf16_f32 v18, v18, v19
	v_cvt_pk_bf16_f32 v19, v20, v21
	v_cvt_pk_bf16_f32 v20, v22, v23
	v_cvt_pk_bf16_f32 v21, v24, v25
	v_mul_f32_e32 v26, v26, v176
	v_mul_f32_e32 v27, v27, v176
	v_mul_f32_e32 v28, v28, v176
	v_mul_f32_e32 v29, v29, v176
	v_mul_f32_e32 v30, v30, v176
	v_mul_f32_e32 v31, v31, v176
	v_mul_f32_e32 v32, v32, v176
	v_mul_f32_e32 v33, v33, v176
	v_cvt_pk_bf16_f32 v26, v26, v27
	v_cvt_pk_bf16_f32 v27, v28, v29
	v_cvt_pk_bf16_f32 v28, v30, v31
	v_cvt_pk_bf16_f32 v29, v32, v33
	v_mul_f32_e32 v2, v2, v176
	v_mul_f32_e32 v3, v3, v176
	v_mul_f32_e32 v4, v4, v176
	v_mul_f32_e32 v5, v5, v176
	v_mul_f32_e32 v6, v6, v176
	v_mul_f32_e32 v7, v7, v176
	v_mul_f32_e32 v8, v8, v176
	v_mul_f32_e32 v9, v9, v176
	v_cvt_pk_bf16_f32 v2, v2, v3
	v_cvt_pk_bf16_f32 v3, v4, v5
	v_cvt_pk_bf16_f32 v4, v6, v7
	v_cvt_pk_bf16_f32 v5, v8, v9
	v_mul_f32_e32 v10, v10, v176
	v_mul_f32_e32 v11, v11, v176
	v_mul_f32_e32 v12, v12, v176
	v_mul_f32_e32 v13, v13, v176
	v_mul_f32_e32 v14, v14, v176
	v_mul_f32_e32 v15, v15, v176
	v_mul_f32_e32 v16, v16, v176
	v_mul_f32_e32 v17, v17, v176
	v_cvt_pk_bf16_f32 v10, v10, v11
	v_cvt_pk_bf16_f32 v11, v12, v13
	v_cvt_pk_bf16_f32 v12, v14, v15
	v_cvt_pk_bf16_f32 v13, v16, v17
	s_nop 1
	v_permlane32_swap_b32_e32 v18, v20
	v_permlane32_swap_b32_e32 v19, v21
	v_permlane32_swap_b32_e32 v26, v28
	v_permlane32_swap_b32_e32 v27, v29
	v_permlane32_swap_b32_e32 v2, v4
	v_permlane32_swap_b32_e32 v3, v5
	v_permlane32_swap_b32_e32 v10, v12
	v_permlane32_swap_b32_e32 v11, v13
	s_and_saveexec_b64 s[10:11], s[40:41]
	s_cbranch_execz .LBB0_521
	v_log_f32_e32 v182, v174
	v_mul_lo_u32 v180, v172, s5
	v_mov_b32_e32 v181, 0
	v_lshl_add_u64 v[180:181], v[180:181], 2, s[8:9]
	v_add_f32_e32 v182, v145, v182
	global_store_dword v[180:181], v182, off
	s_branch .LBB0_521

; #define LAS __attribute__((address_space(3)))
; __global__ void __launch_bounds__(NTHR, 2) fwd_mega(Args args) {
;     extern __shared__ __attribute__((aligned(16))) unsigned char lds_raw[];
;     LAS char* lds = (LAS char*)lds_raw;
;     cg::grid_group grid = cg::this_grid();
;     const int G0 = gridDim.x, bx0 = blockIdx.x;
;     const int vcu0 = (G0 % 8 == 0) ? (bx0 % 8) * (G0 / 8) + bx0 / 8 : bx0;
;     typedef const __attribute__((address_space(4))) Args* KArgs;
;     KArgs ap = (KArgs)__builtin_amdgcn_kernarg_segment_ptr();
;     const int ph_lo = args.ph_lo, ph_hi = args.ph_hi;
;     if (threadIdx.x < 2) ((LAS unsigned*)(lds + LDS_BARW))[threadIdx.x] = 0u;
;     __syncthreads();
;     XcdBarrier bar = xcd_barrier_post((unsigned*)(args.ws + WS_CTL) + 4096, (volatile LAS unsigned*)(lds + LDS_BARW));
;     int probe_done = 0, in_rep = 0;
	.amdhsa_kernel _Z8fwd_mega4Args
		.amdhsa_group_segment_fixed_size 0
		.amdhsa_private_segment_fixed_size 0
		.amdhsa_kernarg_size 448
		.amdhsa_user_sgpr_count 2
		.amdhsa_user_sgpr_dispatch_ptr 0
		.amdhsa_user_sgpr_queue_ptr 0
		.amdhsa_user_sgpr_kernarg_segment_ptr 1
		.amdhsa_user_sgpr_dispatch_id 0
		.amdhsa_user_sgpr_kernarg_preload_length 0
		.amdhsa_user_sgpr_kernarg_preload_offset 0
		.amdhsa_user_sgpr_private_segment_size 0
		.amdhsa_uses_dynamic_stack 0
		.amdhsa_enable_private_segment 0
		.amdhsa_system_sgpr_workgroup_id_x 1
		.amdhsa_system_sgpr_workgroup_id_y 0
		.amdhsa_system_sgpr_workgroup_id_z 0
		.amdhsa_system_sgpr_workgroup_info 0
		.amdhsa_system_vgpr_workitem_id 2
		.amdhsa_next_free_vgpr 256
		.amdhsa_next_free_sgpr 102
		.amdhsa_accum_offset 256
		.amdhsa_reserve_vcc 1
		.amdhsa_float_round_mode_32 0
		.amdhsa_float_round_mode_16_64 0
		.amdhsa_float_denorm_mode_32 3
		.amdhsa_float_denorm_mode_16_64 3
		.amdhsa_dx10_clamp 1
		.amdhsa_ieee_mode 1
		.amdhsa_fp16_overflow 0
		.amdhsa_tg_split 0
		.amdhsa_exception_fp_ieee_invalid_op 0
		.amdhsa_exception_fp_denorm_src 0
		.amdhsa_exception_fp_ieee_div_zero 0
		.amdhsa_exception_fp_ieee_overflow 0
		.amdhsa_exception_fp_ieee_underflow 0
		.amdhsa_exception_fp_ieee_inexact 0
		.amdhsa_exception_int_div_zero 0
	.end_amdhsa_kernel

; #define LAS __attribute__((address_space(3)))
; __global__ void __launch_bounds__(NTHR, 2) fwd_mega(Args args) {
;     extern __shared__ __attribute__((aligned(16))) unsigned char lds_raw[];
;     LAS char* lds = (LAS char*)lds_raw;
;     cg::grid_group grid = cg::this_grid();
;     const int G0 = gridDim.x, bx0 = blockIdx.x;
;     const int vcu0 = (G0 % 8 == 0) ? (bx0 % 8) * (G0 / 8) + bx0 / 8 : bx0;
;     typedef const __attribute__((address_space(4))) Args* KArgs;
;     KArgs ap = (KArgs)__builtin_amdgcn_kernarg_segment_ptr();
;     const int ph_lo = args.ph_lo, ph_hi = args.ph_hi;
;     if (threadIdx.x < 2) ((LAS unsigned*)(lds + LDS_BARW))[threadIdx.x] = 0u;
;     __syncthreads();
;     XcdBarrier bar = xcd_barrier_post((unsigned*)(args.ws + WS_CTL) + 4096, (volatile LAS unsigned*)(lds + LDS_BARW));
;     int probe_done = 0, in_rep = 0;
amdhsa.kernels:
  - .agpr_count:     0
    .args:
      - .offset:         0
        .size:           192
        .value_kind:     by_value
      - .offset:         192
        .size:           4
        .value_kind:     hidden_block_count_x
      - .offset:         196
        .size:           4
        .value_kind:     hidden_block_count_y
      - .offset:         200
        .size:           4
        .value_kind:     hidden_block_count_z
      - .offset:         204
        .size:           2
        .value_kind:     hidden_group_size_x
      - .offset:         206
        .size:           2
        .value_kind:     hidden_group_size_y
      - .offset:         208
        .size:           2
        .value_kind:     hidden_group_size_z
      - .offset:         210
        .size:           2
        .value_kind:     hidden_remainder_x
      - .offset:         212
        .size:           2
        .value_kind:     hidden_remainder_y
      - .offset:         214
        .size:           2
        .value_kind:     hidden_remainder_z
      - .offset:         232
        .size:           8
        .value_kind:     hidden_global_offset_x
      - .offset:         240
        .size:           8
        .value_kind:     hidden_global_offset_y
      - .offset:         248
        .size:           8
        .value_kind:     hidden_global_offset_z
      - .offset:         256
        .size:           2
        .value_kind:     hidden_grid_dims
      - .offset:         280
        .size:           8
        .value_kind:     hidden_multigrid_sync_arg
      - .offset:         312
        .size:           4
        .value_kind:     hidden_dynamic_lds_size
    .group_segment_fixed_size: 0
    .kernarg_segment_align: 8
    .kernarg_segment_size: 448
    .language:       OpenCL C
    .language_version:
      - 2
      - 0
    .max_flat_workgroup_size: 512
    .name:           _Z8fwd_mega4Args
    .private_segment_fixed_size: 0
    .sgpr_count:     108
    .sgpr_spill_count: 158
    .symbol:         _Z8fwd_mega4Args.kd
    .uniform_work_group_size: 1
    .uses_dynamic_stack: false
    .vgpr_count:     256
    .vgpr_spill_count: 0
    .wavefront_size: 64
